# GDN: output from the updated state, beta folded into the staged quad (one fma for u); RET: decay-normalisation factors moved from k/q (64 wide) to v and to the reduced output
# speedup vs baseline: 1.0069x; 1.0069x over previous
.Lls3_16_entry:
	v_and_b32_e32 v124, 63, v196
	v_and_b32_e32 v125, 15, v124
	v_lshrrev_b32_e32 v126, 4, v124
	s_min_u32 s29, s0, 4
	s_mul_i32 s29, s29, 0x5600
	v_and_b32_e32 v127, 3, v125
	v_cmp_eq_u32_e64 s[6:7], 1, v127
	v_cmp_eq_u32_e64 s[8:9], 2, v127
	v_cmp_eq_u32_e64 s[10:11], 3, v127
	v_lshl_add_u32 v0, v125, 4, s29
	v_lshl_add_u32 v1, v126, 4, s29
	s_lshl_b32 s37, s16, 11
	v_lshrrev_b32_e32 v125, 3, v124
	v_and_b32_e32 v126, 7, v124
	v_add_u32_e32 v127, s37, v125
	s_lshl_b32 s21, s17, 7
	s_add_u32 s21, s21, 0x10800700
	v_mul_u32_u24_e32 v5, 0xd00, v127
	v_lshl_add_u32 v5, v126, 4, v5
	v_add_u32_e32 v5, s21, v5
	v_lshlrev_b32_e32 v2, 8, v125
	v_lshl_add_u32 v2, v126, 5, v2
	v_add_u32_e32 v2, s29, v2
	v_and_b32_e32 v125, 31, v124
	v_lshrrev_b32_e32 v126, 2, v125
	v_and_b32_e32 v125, 3, v125
	v_add_u32_e32 v127, s37, v126
	s_lshl_b32 s22, s14, 2
	s_lshl_b32 s21, s17, 6
	s_add_u32 s21, s21, s22
	s_lshl_b32 s44, s21, 1
	s_add_u32 s44, s44, 0x10800b00
	v_mul_u32_u24_e32 v6, 0xd00, v127
	s_lshl_b32 s24, s17, 2
	s_add_u32 s24, s24, 0x13e00600
	v_mul_u32_u24_e32 v8, 0x630, v127
	v_lshl_add_u32 v8, v125, 4, v8
	v_add_u32_e32 v8, s24, v8
	v_lshlrev_b32_e32 v4, 6, v126
	v_lshl_add_u32 v4, v125, 4, v4
	v_lshl_add_u32 v6, v125, 1, v6
	v_add_u32_e32 v6, s44, v6
	v_add_u32_e32 v4, s29, v4
	v_and_b32_e32 v125, 15, v124
	v_lshrrev_b32_e32 v126, 4, v124
	v_add_u32_e32 v127, s37, v124
	v_lshlrev_b32_e32 v7, 11, v127
	s_lshl_b32 s44, s21, 1
	s_add_u32 s44, s44, 0x6300600
	v_add_u32_e32 v7, s44, v7
	s_lshl_b32 s44, s28, 3
	s_add_u32 s44, s44, s16
	s_lshl_b32 s44, s44, 2
	s_add_u32 s44, s44, s17
	s_mul_i32 s44, s44, 0x4000
	s_add_u32 s44, s44, 0x4480000
	s_lshl_b32 s24, s22, 2
	s_add_u32 s44, s44, s24
	v_lshlrev_b32_e32 v130, 10, v125
	v_lshl_add_u32 v130, v126, 2, v130
	v_add_u32_e32 v130, s44, v130
	v_readlane_b32 s26, v253, 29
	v_readlane_b32 s27, v253, 30
	v_lshlrev_b32_e32 v131, 3, v125
	v_lshl_add_u32 v131, v126, 1, v131
	v_add_u32_e32 v131, s29, v131
	v_lshl_add_u32 v132, v124, 3, s29
	v_lshl_add_u32 v133, v124, 2, s29
	v_lshl_add_u32 v131, v124, 1, s29
	v_subrev_u32_e32 v131, 0x100, v131
	v_lshrrev_b32_e32 v125, 2, v124
	v_and_b32_e32 v126, 3, v124
	v_lshlrev_b32_e32 v127, 8, v125
	v_lshl_add_u32 v127, v126, 6, v127
	v_add_u32_e32 v127, s29, v127
	v_add_u32_e32 v126, 0, v125
	v_and_b32_e32 v126, 3, v126
	v_lshl_add_u32 v136, v126, 4, v127
	v_add_u32_e32 v126, 1, v125
	v_and_b32_e32 v126, 3, v126
	v_lshl_add_u32 v137, v126, 4, v127
	v_add_u32_e32 v126, 2, v125
	v_and_b32_e32 v126, 3, v126
	v_lshl_add_u32 v138, v126, 4, v127
	v_add_u32_e32 v126, 3, v125
	v_and_b32_e32 v126, 3, v126
	v_lshl_add_u32 v139, v126, 4, v127
	v_mov_b32_e32 v10, 0
	v_mov_b32_e32 v11, 0
	v_mov_b32_e32 v12, 0
	v_mov_b32_e32 v13, 0
	v_mov_b32_e32 v9, 0
	v_mov_b32_e32 v14, 0
	v_mov_b32_e32 v15, 0
	v_mov_b32_e32 v16, 0
	v_mov_b32_e32 v81, 0
	v_mov_b32_e32 v93, 0
	v_mov_b32_e32 v105, 0
	v_mov_b32_e32 v117, 0
	s_setprio 2
	s_movk_i32 s12, 64
	s_nop 0
	global_load_dwordx4 v[70:73], v5, s[94:95]
	global_load_dwordx4 v[74:77], v5, s[94:95] offset:512
	global_load_ushort v78, v6, s[94:95]
	global_load_dword v79, v8, s[94:95]
	v_add_u32_e32 v5, 0x6800, v5
	v_add_u32_e32 v6, 0x6800, v6
	v_add_u32_e32 v8, 0x3180, v8
	s_waitcnt vmcnt(0)
	s_waitcnt vmcnt(2)
	v_lshlrev_b32_e32 v118, 16, v74
	v_and_b32_e32 v119, 0xffff0000, v74
	v_lshlrev_b32_e32 v120, 16, v75
	v_and_b32_e32 v121, 0xffff0000, v75
	ds_write_b128 v2, v[118:121] offset:0
	v_lshlrev_b32_e32 v124, 16, v76
	v_and_b32_e32 v125, 0xffff0000, v76
	v_lshlrev_b32_e32 v126, 16, v77
	v_and_b32_e32 v127, 0xffff0000, v77
	ds_write_b128 v2, v[124:127] offset:16
	v_lshlrev_b32_e32 v118, 16, v70
	v_and_b32_e32 v119, 0xffff0000, v70
	v_lshlrev_b32_e32 v120, 16, v71
	v_and_b32_e32 v121, 0xffff0000, v71
	ds_write_b128 v2, v[118:121] offset:2048
	v_lshlrev_b32_e32 v124, 16, v72
	v_and_b32_e32 v125, 0xffff0000, v72
	v_lshlrev_b32_e32 v126, 16, v73
	v_and_b32_e32 v127, 0xffff0000, v73
	ds_write_b128 v2, v[124:127] offset:2064
	s_waitcnt vmcnt(0)
	v_mov_b32_dpp v80, v79 quad_perm:[1,1,1,1] row_mask:0xf bank_mask:0xf
	v_mov_b32_dpp v79, v79 quad_perm:[0,0,0,0] row_mask:0xf bank_mask:0xf
	v_lshlrev_b32_e32 v78, 16, v78
	v_mul_f32_e32 v78, v79, v78
	v_mul_f32_e32 v79, v79, v80
	s_nop 0
	ds_write_b128 v4, v[78:81] offset:4096
	global_load_dwordx4 v[82:85], v5, s[94:95]
	global_load_dwordx4 v[86:89], v5, s[94:95] offset:512
	global_load_ushort v90, v6, s[94:95]
	global_load_dword v91, v8, s[94:95]
	v_add_u32_e32 v5, 0x6800, v5
	v_add_u32_e32 v6, 0x6800, v6
	v_add_u32_e32 v8, 0x3180, v8
	global_load_dwordx4 v[94:97], v5, s[94:95]
	global_load_dwordx4 v[98:101], v5, s[94:95] offset:512
	global_load_ushort v102, v6, s[94:95]
	global_load_dword v103, v8, s[94:95]
	v_add_u32_e32 v5, 0x6800, v5
	v_add_u32_e32 v6, 0x6800, v6
	v_add_u32_e32 v8, 0x3180, v8
	global_load_dwordx4 v[106:109], v5, s[94:95]
	global_load_dwordx4 v[110:113], v5, s[94:95] offset:512
	global_load_ushort v114, v6, s[94:95]
	global_load_dword v115, v8, s[94:95]
	v_add_u32_e32 v5, 0x6800, v5
	v_add_u32_e32 v6, 0x6800, v6
	v_add_u32_e32 v8, 0x3180, v8
	global_load_dwordx4 v[70:73], v5, s[94:95]
	global_load_dwordx4 v[74:77], v5, s[94:95] offset:512
	global_load_ushort v78, v6, s[94:95]
	global_load_dword v79, v8, s[94:95]
	v_add_u32_e32 v5, 0x6800, v5
	v_add_u32_e32 v6, 0x6800, v6
	v_add_u32_e32 v8, 0x3180, v8
	ds_read_b128 v[20:23], v0 offset:0
	ds_read_b128 v[38:41], v0 offset:2048
	ds_read_b128 v[54:57], v1 offset:4096
	ds_read_b128 v[24:27], v0 offset:256
	ds_read_b128 v[42:45], v0 offset:2304
	ds_read_b128 v[58:61], v1 offset:4160
	ds_read_b128 v[28:31], v0 offset:512
	ds_read_b128 v[46:49], v0 offset:2560
	ds_read_b128 v[62:65], v1 offset:4224
.Lls3_16_loop:
	s_waitcnt lgkmcnt(6)
	v_mul_f32_e32 v36, v20, v10
	v_fmac_f32_e32 v36, v21, v11
	v_fmac_f32_e32 v36, v22, v12
	v_fmac_f32_e32 v36, v23, v13
	v_mul_f32_e32 v10, v56, v10
	v_mul_f32_e32 v11, v56, v11
	v_add_f32_dpp v36, v36, v36 quad_perm:[1,0,3,2] row_mask:0xf bank_mask:0xf bound_ctrl:1
	v_mul_f32_e32 v12, v56, v12
	v_mul_f32_e32 v13, v56, v13
	v_add_f32_dpp v36, v36, v36 quad_perm:[2,3,0,1] row_mask:0xf bank_mask:0xf bound_ctrl:1
	s_waitcnt vmcnt(14)
	v_lshlrev_b32_e32 v118, 16, v86
	v_add_f32_dpp v36, v36, v36 row_half_mirror row_mask:0xf bank_mask:0xf bound_ctrl:1
	v_and_b32_e32 v119, 0xffff0000, v86
	v_lshlrev_b32_e32 v120, 16, v87
	v_add_f32_dpp v36, v36, v36 row_mirror row_mask:0xf bank_mask:0xf bound_ctrl:1
	v_and_b32_e32 v121, 0xffff0000, v87
	v_fma_f32 v19, -v55, v36, v54
	v_fmac_f32_e32 v10, v20, v19
	v_fmac_f32_e32 v11, v21, v19
	v_fmac_f32_e32 v12, v22, v19
	v_fmac_f32_e32 v13, v23, v19
	v_mul_f32_e32 v122, v38, v10
	v_fmac_f32_e32 v122, v39, v11
	v_fmac_f32_e32 v122, v40, v12
	v_fmac_f32_e32 v122, v41, v13
	ds_write_b32 v133, v122 offset:9216
	ds_read_b128 v[32:35], v0 offset:768
	ds_read_b128 v[50:53], v0 offset:2816
	ds_read_b128 v[66:69], v1 offset:4288
	ds_write_b128 v2, v[118:121] offset:4608
	v_lshlrev_b32_e32 v124, 16, v88
	v_and_b32_e32 v125, 0xffff0000, v88
	s_waitcnt lgkmcnt(8)
	v_mul_f32_e32 v36, v24, v10
	v_fmac_f32_e32 v36, v25, v11
	v_fmac_f32_e32 v36, v26, v12
	v_fmac_f32_e32 v36, v27, v13
	v_mul_f32_e32 v10, v60, v10
	v_mul_f32_e32 v11, v60, v11
	v_add_f32_dpp v36, v36, v36 quad_perm:[1,0,3,2] row_mask:0xf bank_mask:0xf bound_ctrl:1
	v_mul_f32_e32 v12, v60, v12
	v_mul_f32_e32 v13, v60, v13
	v_add_f32_dpp v36, v36, v36 quad_perm:[2,3,0,1] row_mask:0xf bank_mask:0xf bound_ctrl:1
	v_lshlrev_b32_e32 v126, 16, v89
	v_and_b32_e32 v127, 0xffff0000, v89
	v_add_f32_dpp v36, v36, v36 row_half_mirror row_mask:0xf bank_mask:0xf bound_ctrl:1
	ds_write_b128 v2, v[124:127] offset:4624
	v_lshlrev_b32_e32 v118, 16, v82
	v_add_f32_dpp v36, v36, v36 row_mirror row_mask:0xf bank_mask:0xf bound_ctrl:1
	v_and_b32_e32 v119, 0xffff0000, v82
	v_fma_f32 v19, -v59, v36, v58
	v_fmac_f32_e32 v10, v24, v19
	v_fmac_f32_e32 v11, v25, v19
	v_fmac_f32_e32 v12, v26, v19
	v_fmac_f32_e32 v13, v27, v19
	v_mul_f32_e32 v122, v42, v10
	v_fmac_f32_e32 v122, v43, v11
	v_fmac_f32_e32 v122, v44, v12
	v_fmac_f32_e32 v122, v45, v13
	ds_write_b32 v133, v122 offset:9472
	ds_read_b128 v[20:23], v0 offset:1024
	ds_read_b128 v[38:41], v0 offset:3072
	ds_read_b128 v[54:57], v1 offset:4352
	v_lshlrev_b32_e32 v120, 16, v83
	v_and_b32_e32 v121, 0xffff0000, v83
	ds_write_b128 v2, v[118:121] offset:6656
	s_waitcnt lgkmcnt(11)
	v_mul_f32_e32 v36, v28, v10
	v_fmac_f32_e32 v36, v29, v11
	v_fmac_f32_e32 v36, v30, v12
	v_fmac_f32_e32 v36, v31, v13
	v_mul_f32_e32 v10, v64, v10
	v_mul_f32_e32 v11, v64, v11
	v_add_f32_dpp v36, v36, v36 quad_perm:[1,0,3,2] row_mask:0xf bank_mask:0xf bound_ctrl:1
	v_mul_f32_e32 v12, v64, v12
	v_mul_f32_e32 v13, v64, v13
	v_add_f32_dpp v36, v36, v36 quad_perm:[2,3,0,1] row_mask:0xf bank_mask:0xf bound_ctrl:1
	v_lshlrev_b32_e32 v124, 16, v84
	v_and_b32_e32 v125, 0xffff0000, v84
	v_add_f32_dpp v36, v36, v36 row_half_mirror row_mask:0xf bank_mask:0xf bound_ctrl:1
	v_lshlrev_b32_e32 v126, 16, v85
	v_and_b32_e32 v127, 0xffff0000, v85
	v_add_f32_dpp v36, v36, v36 row_mirror row_mask:0xf bank_mask:0xf bound_ctrl:1
	ds_write_b128 v2, v[124:127] offset:6672
	v_fma_f32 v19, -v63, v36, v62
	v_fmac_f32_e32 v10, v28, v19
	v_fmac_f32_e32 v11, v29, v19
	v_fmac_f32_e32 v12, v30, v19
	v_fmac_f32_e32 v13, v31, v19
	v_mul_f32_e32 v122, v46, v10
	v_fmac_f32_e32 v122, v47, v11
	v_fmac_f32_e32 v122, v48, v12
	v_fmac_f32_e32 v122, v49, v13
	ds_write_b32 v133, v122 offset:9728
	ds_read_b128 v[24:27], v0 offset:1280
	ds_read_b128 v[42:45], v0 offset:3328
	ds_read_b128 v[58:61], v1 offset:4416
	s_waitcnt vmcnt(12)
	v_mov_b32_dpp v92, v91 quad_perm:[1,1,1,1] row_mask:0xf bank_mask:0xf
	v_mov_b32_dpp v91, v91 quad_perm:[0,0,0,0] row_mask:0xf bank_mask:0xf
	s_waitcnt lgkmcnt(12)
	v_mul_f32_e32 v36, v32, v10
	v_fmac_f32_e32 v36, v33, v11
	v_fmac_f32_e32 v36, v34, v12
	v_fmac_f32_e32 v36, v35, v13
	v_mul_f32_e32 v10, v68, v10
	v_mul_f32_e32 v11, v68, v11
	v_add_f32_dpp v36, v36, v36 quad_perm:[1,0,3,2] row_mask:0xf bank_mask:0xf bound_ctrl:1
	v_mul_f32_e32 v12, v68, v12
	v_mul_f32_e32 v13, v68, v13
	v_add_f32_dpp v36, v36, v36 quad_perm:[2,3,0,1] row_mask:0xf bank_mask:0xf bound_ctrl:1
	v_lshlrev_b32_e32 v90, 16, v90
	v_mul_f32_e32 v90, v91, v90
	v_add_f32_dpp v36, v36, v36 row_half_mirror row_mask:0xf bank_mask:0xf bound_ctrl:1
	v_mul_f32_e32 v91, v91, v92
	s_nop 0
	v_add_f32_dpp v36, v36, v36 row_mirror row_mask:0xf bank_mask:0xf bound_ctrl:1
	ds_write_b128 v4, v[90:93] offset:8704
	v_fma_f32 v19, -v67, v36, v66
	v_fmac_f32_e32 v10, v32, v19
	v_fmac_f32_e32 v11, v33, v19
	v_fmac_f32_e32 v12, v34, v19
	v_fmac_f32_e32 v13, v35, v19
	v_mul_f32_e32 v122, v50, v10
	v_fmac_f32_e32 v122, v51, v11
	v_fmac_f32_e32 v122, v52, v12
	v_fmac_f32_e32 v122, v53, v13
	ds_write_b32 v133, v122 offset:9984
	ds_read_b128 v[28:31], v0 offset:1536
	ds_read_b128 v[46:49], v0 offset:3584
	ds_read_b128 v[62:65], v1 offset:4480
	s_waitcnt lgkmcnt(11)
	v_mul_f32_e32 v36, v20, v10
	v_fmac_f32_e32 v36, v21, v11
	v_fmac_f32_e32 v36, v22, v12
	v_fmac_f32_e32 v36, v23, v13
	v_mul_f32_e32 v10, v56, v10
	v_mul_f32_e32 v11, v56, v11
	v_add_f32_dpp v36, v36, v36 quad_perm:[1,0,3,2] row_mask:0xf bank_mask:0xf bound_ctrl:1
	v_mul_f32_e32 v12, v56, v12
	v_mul_f32_e32 v13, v56, v13
	v_add_f32_dpp v36, v36, v36 quad_perm:[2,3,0,1] row_mask:0xf bank_mask:0xf bound_ctrl:1
	global_load_dwordx4 v[82:85], v5, s[94:95]
	global_load_dwordx4 v[86:89], v5, s[94:95] offset:512
	global_load_ushort v90, v6, s[94:95]
	global_load_dword v91, v8, s[94:95]
	v_add_u32_e32 v5, 0x6800, v5
	v_add_u32_e32 v6, 0x6800, v6
	v_add_u32_e32 v8, 0x3180, v8
	ds_read_b128 v[140:143], v136 offset:13312
	v_add_f32_dpp v36, v36, v36 row_half_mirror row_mask:0xf bank_mask:0xf bound_ctrl:1
	ds_read_b128 v[154:157], v137 offset:13312
	ds_read_b128 v[158:161], v138 offset:13312
	v_add_f32_dpp v36, v36, v36 row_mirror row_mask:0xf bank_mask:0xf bound_ctrl:1
	ds_read_b128 v[162:165], v139 offset:13312
	v_fma_f32 v19, -v55, v36, v54
	v_fmac_f32_e32 v10, v20, v19
	v_fmac_f32_e32 v11, v21, v19
	v_fmac_f32_e32 v12, v22, v19
	v_fmac_f32_e32 v13, v23, v19
	v_mul_f32_e32 v122, v38, v10
	v_fmac_f32_e32 v122, v39, v11
	v_fmac_f32_e32 v122, v40, v12
	v_fmac_f32_e32 v122, v41, v13
	ds_write_b32 v133, v122 offset:10240
	ds_read_b128 v[32:35], v0 offset:1792
	ds_read_b128 v[50:53], v0 offset:3840
	ds_read_b128 v[66:69], v1 offset:4544
	s_waitcnt lgkmcnt(13)
	v_mul_f32_e32 v36, v24, v10
	v_fmac_f32_e32 v36, v25, v11
	v_fmac_f32_e32 v36, v26, v12
	v_fmac_f32_e32 v36, v27, v13
	v_mul_f32_e32 v10, v60, v10
	v_mul_f32_e32 v11, v60, v11
	v_add_f32_dpp v36, v36, v36 quad_perm:[1,0,3,2] row_mask:0xf bank_mask:0xf bound_ctrl:1
	v_mul_f32_e32 v12, v60, v12
	v_mul_f32_e32 v13, v60, v13
	v_add_f32_dpp v36, v36, v36 quad_perm:[2,3,0,1] row_mask:0xf bank_mask:0xf bound_ctrl:1
	ds_read_b128 v[20:23], v0 offset:4608
	ds_read_b128 v[38:41], v0 offset:6656
	v_add_f32_dpp v36, v36, v36 row_half_mirror row_mask:0xf bank_mask:0xf bound_ctrl:1
	ds_read_b128 v[54:57], v1 offset:8704
	s_nop 0
	v_add_f32_dpp v36, v36, v36 row_mirror row_mask:0xf bank_mask:0xf bound_ctrl:1
	s_nop 0
	v_fma_f32 v19, -v59, v36, v58
	v_fmac_f32_e32 v10, v24, v19
	v_fmac_f32_e32 v11, v25, v19
	v_fmac_f32_e32 v12, v26, v19
	v_fmac_f32_e32 v13, v27, v19
	v_mul_f32_e32 v122, v42, v10
	v_fmac_f32_e32 v122, v43, v11
	v_fmac_f32_e32 v122, v44, v12
	v_fmac_f32_e32 v122, v45, v13
	ds_write_b32 v133, v122 offset:10496
	s_waitcnt lgkmcnt(12)
	v_mul_f32_e32 v36, v28, v10
	v_fmac_f32_e32 v36, v29, v11
	v_fmac_f32_e32 v36, v30, v12
	v_fmac_f32_e32 v36, v31, v13
	v_mul_f32_e32 v10, v64, v10
	v_mul_f32_e32 v11, v64, v11
	v_add_f32_dpp v36, v36, v36 quad_perm:[1,0,3,2] row_mask:0xf bank_mask:0xf bound_ctrl:1
	v_mul_f32_e32 v12, v64, v12
	v_mul_f32_e32 v13, v64, v13
	v_add_f32_dpp v36, v36, v36 quad_perm:[2,3,0,1] row_mask:0xf bank_mask:0xf bound_ctrl:1
	s_waitcnt lgkmcnt(8)
	v_add_f32_e32 v140, v140, v158
	v_add_f32_dpp v36, v36, v36 row_half_mirror row_mask:0xf bank_mask:0xf bound_ctrl:1
	v_add_f32_e32 v141, v141, v159
	v_add_f32_e32 v142, v142, v160
	v_add_f32_dpp v36, v36, v36 row_mirror row_mask:0xf bank_mask:0xf bound_ctrl:1
	v_add_f32_e32 v143, v143, v161
	v_fma_f32 v19, -v63, v36, v62
	v_fmac_f32_e32 v10, v28, v19
	v_fmac_f32_e32 v11, v29, v19
	v_fmac_f32_e32 v12, v30, v19
	v_fmac_f32_e32 v13, v31, v19
	v_mul_f32_e32 v122, v46, v10
	v_fmac_f32_e32 v122, v47, v11
	v_fmac_f32_e32 v122, v48, v12
	v_fmac_f32_e32 v122, v49, v13
	ds_write_b32 v133, v122 offset:10752
	ds_read_b128 v[24:27], v0 offset:4864
	ds_read_b128 v[42:45], v0 offset:6912
	ds_read_b128 v[58:61], v1 offset:8768
	v_add_f32_e32 v154, v154, v162
	v_add_f32_e32 v155, v155, v163
	v_add_f32_e32 v156, v156, v164
	v_add_f32_e32 v157, v157, v165
	v_add_f32_e32 v140, v140, v154
	v_add_f32_e32 v141, v141, v155
	v_add_f32_e32 v142, v142, v156
	v_add_f32_e32 v143, v143, v157
	v_add_f32_e32 v140, v140, v141
	v_add_f32_e32 v142, v142, v143
	v_add_f32_e32 v140, v140, v142
	v_cvt_pk_bf16_f32 v18, v140, v140
	ds_write_b16 v131, v18 offset:17792
	v_add_u32_e32 v131, 0x100, v131
	s_and_b32 s24, s12, 15
	s_cmp_eq_u32 s24, 0
	s_cbranch_scc0 .Lls3_16_noflush
	s_cmp_eq_u32 s12, 64
	s_cbranch_scc1 .Lls3_16_noflush
	s_waitcnt lgkmcnt(0)
	ds_read_b64 v[134:135], v132 offset:17664
	s_waitcnt lgkmcnt(0)
	global_store_dwordx2 v7, v[134:135], s[94:95]
	v_add_u32_e32 v7, 0x20000, v7
	s_nop 0
	ds_read_b64 v[134:135], v132 offset:18176
	s_waitcnt lgkmcnt(0)
	global_store_dwordx2 v7, v[134:135], s[94:95]
	v_add_u32_e32 v7, 0x20000, v7
	s_nop 0
	ds_read_b64 v[134:135], v132 offset:18688
	s_waitcnt lgkmcnt(0)
	global_store_dwordx2 v7, v[134:135], s[94:95]
	v_add_u32_e32 v7, 0x20000, v7
	s_nop 0
	ds_read_b64 v[134:135], v132 offset:19200
	s_waitcnt lgkmcnt(0)
	global_store_dwordx2 v7, v[134:135], s[94:95]
	v_add_u32_e32 v7, 0x20000, v7
	s_nop 0
	ds_read_b64 v[134:135], v132 offset:19712
	s_waitcnt lgkmcnt(0)
	global_store_dwordx2 v7, v[134:135], s[94:95]
	v_add_u32_e32 v7, 0x20000, v7
	s_nop 0
	ds_read_b64 v[134:135], v132 offset:20224
	s_waitcnt lgkmcnt(0)
	global_store_dwordx2 v7, v[134:135], s[94:95]
	v_add_u32_e32 v7, 0x20000, v7
	s_nop 0
	ds_read_b64 v[134:135], v132 offset:20736
	s_waitcnt lgkmcnt(0)
	global_store_dwordx2 v7, v[134:135], s[94:95]
	v_add_u32_e32 v7, 0x20000, v7
	s_nop 0
	ds_read_b64 v[134:135], v132 offset:21248
	s_waitcnt lgkmcnt(0)
	global_store_dwordx2 v7, v[134:135], s[94:95]
	v_add_u32_e32 v7, 0x20000, v7
	s_nop 0
	v_subrev_u32_e32 v131, 0x1000, v131
.Lls3_16_noflush:
	s_waitcnt lgkmcnt(9)
	v_mul_f32_e32 v36, v32, v10
	v_fmac_f32_e32 v36, v33, v11
	v_fmac_f32_e32 v36, v34, v12
	v_fmac_f32_e32 v36, v35, v13
	v_mul_f32_e32 v10, v68, v10
	v_mul_f32_e32 v11, v68, v11
	v_add_f32_dpp v36, v36, v36 quad_perm:[1,0,3,2] row_mask:0xf bank_mask:0xf bound_ctrl:1
	v_mul_f32_e32 v12, v68, v12
	v_mul_f32_e32 v13, v68, v13
	v_add_f32_dpp v36, v36, v36 quad_perm:[2,3,0,1] row_mask:0xf bank_mask:0xf bound_ctrl:1
	ds_read_b128 v[28:31], v0 offset:5120
	ds_read_b128 v[46:49], v0 offset:7168
	v_add_f32_dpp v36, v36, v36 row_half_mirror row_mask:0xf bank_mask:0xf bound_ctrl:1
	ds_read_b128 v[62:65], v1 offset:8832
	s_nop 0
	v_add_f32_dpp v36, v36, v36 row_mirror row_mask:0xf bank_mask:0xf bound_ctrl:1
	s_nop 0
	v_fma_f32 v19, -v67, v36, v66
	v_fmac_f32_e32 v10, v32, v19
	v_fmac_f32_e32 v11, v33, v19
	v_fmac_f32_e32 v12, v34, v19
	v_fmac_f32_e32 v13, v35, v19
	v_mul_f32_e32 v122, v50, v10
	v_fmac_f32_e32 v122, v51, v11
	v_fmac_f32_e32 v122, v52, v12
	v_fmac_f32_e32 v122, v53, v13
	ds_write_b32 v133, v122 offset:11008
	s_waitcnt lgkmcnt(10)
	v_mul_f32_e32 v36, v20, v10
	v_fmac_f32_e32 v36, v21, v11
	v_fmac_f32_e32 v36, v22, v12
	v_fmac_f32_e32 v36, v23, v13
	v_mul_f32_e32 v10, v56, v10
	v_mul_f32_e32 v11, v56, v11
	v_add_f32_dpp v36, v36, v36 quad_perm:[1,0,3,2] row_mask:0xf bank_mask:0xf bound_ctrl:1
	v_mul_f32_e32 v12, v56, v12
	v_mul_f32_e32 v13, v56, v13
	v_add_f32_dpp v36, v36, v36 quad_perm:[2,3,0,1] row_mask:0xf bank_mask:0xf bound_ctrl:1
	s_waitcnt vmcnt(14)
	v_lshlrev_b32_e32 v118, 16, v98
	v_add_f32_dpp v36, v36, v36 row_half_mirror row_mask:0xf bank_mask:0xf bound_ctrl:1
	v_and_b32_e32 v119, 0xffff0000, v98
	v_lshlrev_b32_e32 v120, 16, v99
	v_add_f32_dpp v36, v36, v36 row_mirror row_mask:0xf bank_mask:0xf bound_ctrl:1
	v_and_b32_e32 v121, 0xffff0000, v99
	v_fma_f32 v19, -v55, v36, v54
	v_fmac_f32_e32 v10, v20, v19
	v_fmac_f32_e32 v11, v21, v19
	v_fmac_f32_e32 v12, v22, v19
	v_fmac_f32_e32 v13, v23, v19
	v_mul_f32_e32 v122, v38, v10
	v_fmac_f32_e32 v122, v39, v11
	v_fmac_f32_e32 v122, v40, v12
	v_fmac_f32_e32 v122, v41, v13
	ds_write_b32 v133, v122 offset:11264
	ds_read_b128 v[32:35], v0 offset:5376
	ds_read_b128 v[50:53], v0 offset:7424
	ds_read_b128 v[66:69], v1 offset:8896
	ds_write_b128 v2, v[118:121] offset:0
	v_lshlrev_b32_e32 v124, 16, v100
	v_and_b32_e32 v125, 0xffff0000, v100
	s_waitcnt lgkmcnt(10)
	v_mul_f32_e32 v36, v24, v10
	v_fmac_f32_e32 v36, v25, v11
	v_fmac_f32_e32 v36, v26, v12
	v_fmac_f32_e32 v36, v27, v13
	v_mul_f32_e32 v10, v60, v10
	v_mul_f32_e32 v11, v60, v11
	v_add_f32_dpp v36, v36, v36 quad_perm:[1,0,3,2] row_mask:0xf bank_mask:0xf bound_ctrl:1
	v_mul_f32_e32 v12, v60, v12
	v_mul_f32_e32 v13, v60, v13
	v_add_f32_dpp v36, v36, v36 quad_perm:[2,3,0,1] row_mask:0xf bank_mask:0xf bound_ctrl:1
	v_lshlrev_b32_e32 v126, 16, v101
	v_and_b32_e32 v127, 0xffff0000, v101
	v_add_f32_dpp v36, v36, v36 row_half_mirror row_mask:0xf bank_mask:0xf bound_ctrl:1
	ds_write_b128 v2, v[124:127] offset:16
	v_lshlrev_b32_e32 v118, 16, v94
	v_add_f32_dpp v36, v36, v36 row_mirror row_mask:0xf bank_mask:0xf bound_ctrl:1
	v_and_b32_e32 v119, 0xffff0000, v94
	v_fma_f32 v19, -v59, v36, v58
	v_fmac_f32_e32 v10, v24, v19
	v_fmac_f32_e32 v11, v25, v19
	v_fmac_f32_e32 v12, v26, v19
	v_fmac_f32_e32 v13, v27, v19
	v_mul_f32_e32 v122, v42, v10
	v_fmac_f32_e32 v122, v43, v11
	v_fmac_f32_e32 v122, v44, v12
	v_fmac_f32_e32 v122, v45, v13
	ds_write_b32 v133, v122 offset:11520
	ds_read_b128 v[20:23], v0 offset:5632
	ds_read_b128 v[38:41], v0 offset:7680
	ds_read_b128 v[54:57], v1 offset:8960
	v_lshlrev_b32_e32 v120, 16, v95
	v_and_b32_e32 v121, 0xffff0000, v95
	ds_write_b128 v2, v[118:121] offset:2048
	s_waitcnt lgkmcnt(12)
	v_mul_f32_e32 v36, v28, v10
	v_fmac_f32_e32 v36, v29, v11
	v_fmac_f32_e32 v36, v30, v12
	v_fmac_f32_e32 v36, v31, v13
	v_mul_f32_e32 v10, v64, v10
	v_mul_f32_e32 v11, v64, v11
	v_add_f32_dpp v36, v36, v36 quad_perm:[1,0,3,2] row_mask:0xf bank_mask:0xf bound_ctrl:1
	v_mul_f32_e32 v12, v64, v12
	v_mul_f32_e32 v13, v64, v13
	v_add_f32_dpp v36, v36, v36 quad_perm:[2,3,0,1] row_mask:0xf bank_mask:0xf bound_ctrl:1
	v_lshlrev_b32_e32 v124, 16, v96
	v_and_b32_e32 v125, 0xffff0000, v96
	v_add_f32_dpp v36, v36, v36 row_half_mirror row_mask:0xf bank_mask:0xf bound_ctrl:1
	v_lshlrev_b32_e32 v126, 16, v97
	v_and_b32_e32 v127, 0xffff0000, v97
	v_add_f32_dpp v36, v36, v36 row_mirror row_mask:0xf bank_mask:0xf bound_ctrl:1
	ds_write_b128 v2, v[124:127] offset:2064
	v_fma_f32 v19, -v63, v36, v62
	v_fmac_f32_e32 v10, v28, v19
	v_fmac_f32_e32 v11, v29, v19
	v_fmac_f32_e32 v12, v30, v19
	v_fmac_f32_e32 v13, v31, v19
	v_mul_f32_e32 v122, v46, v10
	v_fmac_f32_e32 v122, v47, v11
	v_fmac_f32_e32 v122, v48, v12
	v_fmac_f32_e32 v122, v49, v13
	ds_write_b32 v133, v122 offset:11776
	ds_read_b128 v[24:27], v0 offset:5888
	ds_read_b128 v[42:45], v0 offset:7936
	ds_read_b128 v[58:61], v1 offset:9024
	s_waitcnt vmcnt(12)
	v_mov_b32_dpp v104, v103 quad_perm:[1,1,1,1] row_mask:0xf bank_mask:0xf
	v_mov_b32_dpp v103, v103 quad_perm:[0,0,0,0] row_mask:0xf bank_mask:0xf
	s_waitcnt lgkmcnt(12)
	v_mul_f32_e32 v36, v32, v10
	v_fmac_f32_e32 v36, v33, v11
	v_fmac_f32_e32 v36, v34, v12
	v_fmac_f32_e32 v36, v35, v13
	v_mul_f32_e32 v10, v68, v10
	v_mul_f32_e32 v11, v68, v11
	v_add_f32_dpp v36, v36, v36 quad_perm:[1,0,3,2] row_mask:0xf bank_mask:0xf bound_ctrl:1
	v_mul_f32_e32 v12, v68, v12
	v_mul_f32_e32 v13, v68, v13
	v_add_f32_dpp v36, v36, v36 quad_perm:[2,3,0,1] row_mask:0xf bank_mask:0xf bound_ctrl:1
	v_lshlrev_b32_e32 v102, 16, v102
	v_mul_f32_e32 v102, v103, v102
	v_add_f32_dpp v36, v36, v36 row_half_mirror row_mask:0xf bank_mask:0xf bound_ctrl:1
	v_mul_f32_e32 v103, v103, v104
	s_nop 0
	v_add_f32_dpp v36, v36, v36 row_mirror row_mask:0xf bank_mask:0xf bound_ctrl:1
	ds_write_b128 v4, v[102:105] offset:4096
	v_fma_f32 v19, -v67, v36, v66
	v_fmac_f32_e32 v10, v32, v19
	v_fmac_f32_e32 v11, v33, v19
	v_fmac_f32_e32 v12, v34, v19
	v_fmac_f32_e32 v13, v35, v19
	v_mul_f32_e32 v122, v50, v10
	v_fmac_f32_e32 v122, v51, v11
	v_fmac_f32_e32 v122, v52, v12
	v_fmac_f32_e32 v122, v53, v13
	ds_write_b32 v133, v122 offset:12032
	ds_read_b128 v[28:31], v0 offset:6144
	ds_read_b128 v[46:49], v0 offset:8192
	ds_read_b128 v[62:65], v1 offset:9088
	s_waitcnt lgkmcnt(11)
	v_mul_f32_e32 v36, v20, v10
	v_fmac_f32_e32 v36, v21, v11
	v_fmac_f32_e32 v36, v22, v12
	v_fmac_f32_e32 v36, v23, v13
	v_mul_f32_e32 v10, v56, v10
	v_mul_f32_e32 v11, v56, v11
	v_add_f32_dpp v36, v36, v36 quad_perm:[1,0,3,2] row_mask:0xf bank_mask:0xf bound_ctrl:1
	v_mul_f32_e32 v12, v56, v12
	v_mul_f32_e32 v13, v56, v13
	v_add_f32_dpp v36, v36, v36 quad_perm:[2,3,0,1] row_mask:0xf bank_mask:0xf bound_ctrl:1
	global_load_dwordx4 v[94:97], v5, s[94:95]
	global_load_dwordx4 v[98:101], v5, s[94:95] offset:512
	global_load_ushort v102, v6, s[94:95]
	global_load_dword v103, v8, s[94:95]
	v_add_u32_e32 v5, 0x6800, v5
	v_add_u32_e32 v6, 0x6800, v6
	v_add_u32_e32 v8, 0x3180, v8
	ds_read_b128 v[32:35], v0 offset:6400
	v_add_f32_dpp v36, v36, v36 row_half_mirror row_mask:0xf bank_mask:0xf bound_ctrl:1
	ds_read_b128 v[50:53], v0 offset:8448
	ds_read_b128 v[66:69], v1 offset:9152
	v_add_f32_dpp v36, v36, v36 row_mirror row_mask:0xf bank_mask:0xf bound_ctrl:1
	s_nop 0
	v_fma_f32 v19, -v55, v36, v54
	v_fmac_f32_e32 v10, v20, v19
	v_fmac_f32_e32 v11, v21, v19
	v_fmac_f32_e32 v12, v22, v19
	v_fmac_f32_e32 v13, v23, v19
	v_mul_f32_e32 v122, v38, v10
	v_fmac_f32_e32 v122, v39, v11
	v_fmac_f32_e32 v122, v40, v12
	v_fmac_f32_e32 v122, v41, v13
	ds_write_b32 v133, v122 offset:12288
	s_waitcnt lgkmcnt(9)
	v_mul_f32_e32 v36, v24, v10
	v_fmac_f32_e32 v36, v25, v11
	v_fmac_f32_e32 v36, v26, v12
	v_fmac_f32_e32 v36, v27, v13
	v_mul_f32_e32 v10, v60, v10
	v_mul_f32_e32 v11, v60, v11
	v_add_f32_dpp v36, v36, v36 quad_perm:[1,0,3,2] row_mask:0xf bank_mask:0xf bound_ctrl:1
	v_mul_f32_e32 v12, v60, v12
	v_mul_f32_e32 v13, v60, v13
	v_add_f32_dpp v36, v36, v36 quad_perm:[2,3,0,1] row_mask:0xf bank_mask:0xf bound_ctrl:1
	ds_read_b128 v[20:23], v0 offset:0
	ds_read_b128 v[38:41], v0 offset:2048
	v_add_f32_dpp v36, v36, v36 row_half_mirror row_mask:0xf bank_mask:0xf bound_ctrl:1
	ds_read_b128 v[54:57], v1 offset:4096
	s_nop 0
	v_add_f32_dpp v36, v36, v36 row_mirror row_mask:0xf bank_mask:0xf bound_ctrl:1
	s_nop 0
	v_fma_f32 v19, -v59, v36, v58
	v_fmac_f32_e32 v10, v24, v19
	v_fmac_f32_e32 v11, v25, v19
	v_fmac_f32_e32 v12, v26, v19
	v_fmac_f32_e32 v13, v27, v19
	v_mul_f32_e32 v122, v42, v10
	v_fmac_f32_e32 v122, v43, v11
	v_fmac_f32_e32 v122, v44, v12
	v_fmac_f32_e32 v122, v45, v13
	ds_write_b32 v133, v122 offset:12544
	s_waitcnt lgkmcnt(8)
	v_mul_f32_e32 v36, v28, v10
	v_fmac_f32_e32 v36, v29, v11
	v_fmac_f32_e32 v36, v30, v12
	v_fmac_f32_e32 v36, v31, v13
	v_mul_f32_e32 v10, v64, v10
	v_mul_f32_e32 v11, v64, v11
	v_add_f32_dpp v36, v36, v36 quad_perm:[1,0,3,2] row_mask:0xf bank_mask:0xf bound_ctrl:1
	v_mul_f32_e32 v12, v64, v12
	v_mul_f32_e32 v13, v64, v13
	v_add_f32_dpp v36, v36, v36 quad_perm:[2,3,0,1] row_mask:0xf bank_mask:0xf bound_ctrl:1
	ds_read_b128 v[24:27], v0 offset:256
	ds_read_b128 v[42:45], v0 offset:2304
	v_add_f32_dpp v36, v36, v36 row_half_mirror row_mask:0xf bank_mask:0xf bound_ctrl:1
	ds_read_b128 v[58:61], v1 offset:4160
	s_nop 0
	v_add_f32_dpp v36, v36, v36 row_mirror row_mask:0xf bank_mask:0xf bound_ctrl:1
	s_nop 0
	v_fma_f32 v19, -v63, v36, v62
	v_fmac_f32_e32 v10, v28, v19
	v_fmac_f32_e32 v11, v29, v19
	v_fmac_f32_e32 v12, v30, v19
	v_fmac_f32_e32 v13, v31, v19
	v_mul_f32_e32 v122, v46, v10
	v_fmac_f32_e32 v122, v47, v11
	v_fmac_f32_e32 v122, v48, v12
	v_fmac_f32_e32 v122, v49, v13
	ds_write_b32 v133, v122 offset:12800
	s_waitcnt lgkmcnt(9)
	v_mul_f32_e32 v36, v32, v10
	v_fmac_f32_e32 v36, v33, v11
	v_fmac_f32_e32 v36, v34, v12
	v_fmac_f32_e32 v36, v35, v13
	v_mul_f32_e32 v10, v68, v10
	v_mul_f32_e32 v11, v68, v11
	v_add_f32_dpp v36, v36, v36 quad_perm:[1,0,3,2] row_mask:0xf bank_mask:0xf bound_ctrl:1
	v_mul_f32_e32 v12, v68, v12
	v_mul_f32_e32 v13, v68, v13
	v_add_f32_dpp v36, v36, v36 quad_perm:[2,3,0,1] row_mask:0xf bank_mask:0xf bound_ctrl:1
	ds_read_b128 v[28:31], v0 offset:512
	ds_read_b128 v[46:49], v0 offset:2560
	v_add_f32_dpp v36, v36, v36 row_half_mirror row_mask:0xf bank_mask:0xf bound_ctrl:1
	ds_read_b128 v[62:65], v1 offset:4224
	s_nop 0
	v_add_f32_dpp v36, v36, v36 row_mirror row_mask:0xf bank_mask:0xf bound_ctrl:1
	s_nop 0
	v_fma_f32 v19, -v67, v36, v66
	v_fmac_f32_e32 v10, v32, v19
	v_fmac_f32_e32 v11, v33, v19
	v_fmac_f32_e32 v12, v34, v19
	v_fmac_f32_e32 v13, v35, v19
	v_mul_f32_e32 v122, v50, v10
	v_fmac_f32_e32 v122, v51, v11
	v_fmac_f32_e32 v122, v52, v12
	v_fmac_f32_e32 v122, v53, v13
	ds_write_b32 v133, v122 offset:13056
	s_waitcnt lgkmcnt(9)
	v_mul_f32_e32 v36, v20, v10
	v_fmac_f32_e32 v36, v21, v11
	v_fmac_f32_e32 v36, v22, v12
	v_fmac_f32_e32 v36, v23, v13
	v_mul_f32_e32 v10, v56, v10
	v_mul_f32_e32 v11, v56, v11
	v_add_f32_dpp v36, v36, v36 quad_perm:[1,0,3,2] row_mask:0xf bank_mask:0xf bound_ctrl:1
	v_mul_f32_e32 v12, v56, v12
	v_mul_f32_e32 v13, v56, v13
	v_add_f32_dpp v36, v36, v36 quad_perm:[2,3,0,1] row_mask:0xf bank_mask:0xf bound_ctrl:1
	s_waitcnt vmcnt(14)
	v_lshlrev_b32_e32 v118, 16, v110
	v_add_f32_dpp v36, v36, v36 row_half_mirror row_mask:0xf bank_mask:0xf bound_ctrl:1
	v_and_b32_e32 v119, 0xffff0000, v110
	v_lshlrev_b32_e32 v120, 16, v111
	v_add_f32_dpp v36, v36, v36 row_mirror row_mask:0xf bank_mask:0xf bound_ctrl:1
	v_and_b32_e32 v121, 0xffff0000, v111
	v_fma_f32 v19, -v55, v36, v54
	v_fmac_f32_e32 v10, v20, v19
	v_fmac_f32_e32 v11, v21, v19
	v_fmac_f32_e32 v12, v22, v19
	v_fmac_f32_e32 v13, v23, v19
	v_mul_f32_e32 v122, v38, v10
	v_fmac_f32_e32 v122, v39, v11
	v_fmac_f32_e32 v122, v40, v12
	v_fmac_f32_e32 v122, v41, v13
	ds_write_b32 v133, v122 offset:13312
	ds_read_b128 v[32:35], v0 offset:768
	ds_read_b128 v[50:53], v0 offset:2816
	ds_read_b128 v[66:69], v1 offset:4288
	ds_write_b128 v2, v[118:121] offset:4608
	v_lshlrev_b32_e32 v124, 16, v112
	v_and_b32_e32 v125, 0xffff0000, v112
	s_waitcnt lgkmcnt(10)
	v_mul_f32_e32 v36, v24, v10
	v_fmac_f32_e32 v36, v25, v11
	v_fmac_f32_e32 v36, v26, v12
	v_fmac_f32_e32 v36, v27, v13
	v_mul_f32_e32 v10, v60, v10
	v_mul_f32_e32 v11, v60, v11
	v_add_f32_dpp v36, v36, v36 quad_perm:[1,0,3,2] row_mask:0xf bank_mask:0xf bound_ctrl:1
	v_mul_f32_e32 v12, v60, v12
	v_mul_f32_e32 v13, v60, v13
	v_add_f32_dpp v36, v36, v36 quad_perm:[2,3,0,1] row_mask:0xf bank_mask:0xf bound_ctrl:1
	v_lshlrev_b32_e32 v126, 16, v113
	v_and_b32_e32 v127, 0xffff0000, v113
	v_add_f32_dpp v36, v36, v36 row_half_mirror row_mask:0xf bank_mask:0xf bound_ctrl:1
	ds_write_b128 v2, v[124:127] offset:4624
	v_lshlrev_b32_e32 v118, 16, v106
	v_add_f32_dpp v36, v36, v36 row_mirror row_mask:0xf bank_mask:0xf bound_ctrl:1
	v_and_b32_e32 v119, 0xffff0000, v106
	v_fma_f32 v19, -v59, v36, v58
	v_fmac_f32_e32 v10, v24, v19
	v_fmac_f32_e32 v11, v25, v19
	v_fmac_f32_e32 v12, v26, v19
	v_fmac_f32_e32 v13, v27, v19
	v_mul_f32_e32 v122, v42, v10
	v_fmac_f32_e32 v122, v43, v11
	v_fmac_f32_e32 v122, v44, v12
	v_fmac_f32_e32 v122, v45, v13
	ds_write_b32 v133, v122 offset:13568
	ds_read_b128 v[20:23], v0 offset:1024
	ds_read_b128 v[38:41], v0 offset:3072
	ds_read_b128 v[54:57], v1 offset:4352
	v_lshlrev_b32_e32 v120, 16, v107
	v_and_b32_e32 v121, 0xffff0000, v107
	ds_write_b128 v2, v[118:121] offset:6656
	s_waitcnt lgkmcnt(12)
	v_mul_f32_e32 v36, v28, v10
	v_fmac_f32_e32 v36, v29, v11
	v_fmac_f32_e32 v36, v30, v12
	v_fmac_f32_e32 v36, v31, v13
	v_mul_f32_e32 v10, v64, v10
	v_mul_f32_e32 v11, v64, v11
	v_add_f32_dpp v36, v36, v36 quad_perm:[1,0,3,2] row_mask:0xf bank_mask:0xf bound_ctrl:1
	v_mul_f32_e32 v12, v64, v12
	v_mul_f32_e32 v13, v64, v13
	v_add_f32_dpp v36, v36, v36 quad_perm:[2,3,0,1] row_mask:0xf bank_mask:0xf bound_ctrl:1
	v_lshlrev_b32_e32 v124, 16, v108
	v_and_b32_e32 v125, 0xffff0000, v108
	v_add_f32_dpp v36, v36, v36 row_half_mirror row_mask:0xf bank_mask:0xf bound_ctrl:1
	v_lshlrev_b32_e32 v126, 16, v109
	v_and_b32_e32 v127, 0xffff0000, v109
	v_add_f32_dpp v36, v36, v36 row_mirror row_mask:0xf bank_mask:0xf bound_ctrl:1
	ds_write_b128 v2, v[124:127] offset:6672
	v_fma_f32 v19, -v63, v36, v62
	v_fmac_f32_e32 v10, v28, v19
	v_fmac_f32_e32 v11, v29, v19
	v_fmac_f32_e32 v12, v30, v19
	v_fmac_f32_e32 v13, v31, v19
	v_mul_f32_e32 v122, v46, v10
	v_fmac_f32_e32 v122, v47, v11
	v_fmac_f32_e32 v122, v48, v12
	v_fmac_f32_e32 v122, v49, v13
	ds_write_b32 v133, v122 offset:13824
	ds_read_b128 v[24:27], v0 offset:1280
	ds_read_b128 v[42:45], v0 offset:3328
	ds_read_b128 v[58:61], v1 offset:4416
	s_waitcnt vmcnt(12)
	v_mov_b32_dpp v116, v115 quad_perm:[1,1,1,1] row_mask:0xf bank_mask:0xf
	v_mov_b32_dpp v115, v115 quad_perm:[0,0,0,0] row_mask:0xf bank_mask:0xf
	s_waitcnt lgkmcnt(12)
	v_mul_f32_e32 v36, v32, v10
	v_fmac_f32_e32 v36, v33, v11
	v_fmac_f32_e32 v36, v34, v12
	v_fmac_f32_e32 v36, v35, v13
	v_mul_f32_e32 v10, v68, v10
	v_mul_f32_e32 v11, v68, v11
	v_add_f32_dpp v36, v36, v36 quad_perm:[1,0,3,2] row_mask:0xf bank_mask:0xf bound_ctrl:1
	v_mul_f32_e32 v12, v68, v12
	v_mul_f32_e32 v13, v68, v13
	v_add_f32_dpp v36, v36, v36 quad_perm:[2,3,0,1] row_mask:0xf bank_mask:0xf bound_ctrl:1
	v_lshlrev_b32_e32 v114, 16, v114
	v_mul_f32_e32 v114, v115, v114
	v_add_f32_dpp v36, v36, v36 row_half_mirror row_mask:0xf bank_mask:0xf bound_ctrl:1
	v_mul_f32_e32 v115, v115, v116
	s_nop 0
	v_add_f32_dpp v36, v36, v36 row_mirror row_mask:0xf bank_mask:0xf bound_ctrl:1
	ds_write_b128 v4, v[114:117] offset:8704
	v_fma_f32 v19, -v67, v36, v66
	v_fmac_f32_e32 v10, v32, v19
	v_fmac_f32_e32 v11, v33, v19
	v_fmac_f32_e32 v12, v34, v19
	v_fmac_f32_e32 v13, v35, v19
	v_mul_f32_e32 v122, v50, v10
	v_fmac_f32_e32 v122, v51, v11
	v_fmac_f32_e32 v122, v52, v12
	v_fmac_f32_e32 v122, v53, v13
	ds_write_b32 v133, v122 offset:14080
	ds_read_b128 v[28:31], v0 offset:1536
	ds_read_b128 v[46:49], v0 offset:3584
	ds_read_b128 v[62:65], v1 offset:4480
	s_waitcnt lgkmcnt(11)
	v_mul_f32_e32 v36, v20, v10
	v_fmac_f32_e32 v36, v21, v11
	v_fmac_f32_e32 v36, v22, v12
	v_fmac_f32_e32 v36, v23, v13
	v_mul_f32_e32 v10, v56, v10
	v_mul_f32_e32 v11, v56, v11
	v_add_f32_dpp v36, v36, v36 quad_perm:[1,0,3,2] row_mask:0xf bank_mask:0xf bound_ctrl:1
	v_mul_f32_e32 v12, v56, v12
	v_mul_f32_e32 v13, v56, v13
	v_add_f32_dpp v36, v36, v36 quad_perm:[2,3,0,1] row_mask:0xf bank_mask:0xf bound_ctrl:1
	global_load_dwordx4 v[106:109], v5, s[94:95]
	global_load_dwordx4 v[110:113], v5, s[94:95] offset:512
	global_load_ushort v114, v6, s[94:95]
	global_load_dword v115, v8, s[94:95]
	v_add_u32_e32 v5, 0x6800, v5
	v_add_u32_e32 v6, 0x6800, v6
	v_add_u32_e32 v8, 0x3180, v8
	ds_read_b128 v[140:143], v136 offset:9216
	v_add_f32_dpp v36, v36, v36 row_half_mirror row_mask:0xf bank_mask:0xf bound_ctrl:1
	ds_read_b128 v[154:157], v137 offset:9216
	ds_read_b128 v[158:161], v138 offset:9216
	v_add_f32_dpp v36, v36, v36 row_mirror row_mask:0xf bank_mask:0xf bound_ctrl:1
	ds_read_b128 v[162:165], v139 offset:9216
	v_fma_f32 v19, -v55, v36, v54
	v_fmac_f32_e32 v10, v20, v19
	v_fmac_f32_e32 v11, v21, v19
	v_fmac_f32_e32 v12, v22, v19
	v_fmac_f32_e32 v13, v23, v19
	v_mul_f32_e32 v122, v38, v10
	v_fmac_f32_e32 v122, v39, v11
	v_fmac_f32_e32 v122, v40, v12
	v_fmac_f32_e32 v122, v41, v13
	ds_write_b32 v133, v122 offset:14336
	ds_read_b128 v[32:35], v0 offset:1792
	ds_read_b128 v[50:53], v0 offset:3840
	ds_read_b128 v[66:69], v1 offset:4544
	s_waitcnt lgkmcnt(13)
	v_mul_f32_e32 v36, v24, v10
	v_fmac_f32_e32 v36, v25, v11
	v_fmac_f32_e32 v36, v26, v12
	v_fmac_f32_e32 v36, v27, v13
	v_mul_f32_e32 v10, v60, v10
	v_mul_f32_e32 v11, v60, v11
	v_add_f32_dpp v36, v36, v36 quad_perm:[1,0,3,2] row_mask:0xf bank_mask:0xf bound_ctrl:1
	v_mul_f32_e32 v12, v60, v12
	v_mul_f32_e32 v13, v60, v13
	v_add_f32_dpp v36, v36, v36 quad_perm:[2,3,0,1] row_mask:0xf bank_mask:0xf bound_ctrl:1
	ds_read_b128 v[20:23], v0 offset:4608
	ds_read_b128 v[38:41], v0 offset:6656
	v_add_f32_dpp v36, v36, v36 row_half_mirror row_mask:0xf bank_mask:0xf bound_ctrl:1
	ds_read_b128 v[54:57], v1 offset:8704
	s_nop 0
	v_add_f32_dpp v36, v36, v36 row_mirror row_mask:0xf bank_mask:0xf bound_ctrl:1
	s_nop 0
	v_fma_f32 v19, -v59, v36, v58
	v_fmac_f32_e32 v10, v24, v19
	v_fmac_f32_e32 v11, v25, v19
	v_fmac_f32_e32 v12, v26, v19
	v_fmac_f32_e32 v13, v27, v19
	v_mul_f32_e32 v122, v42, v10
	v_fmac_f32_e32 v122, v43, v11
	v_fmac_f32_e32 v122, v44, v12
	v_fmac_f32_e32 v122, v45, v13
	ds_write_b32 v133, v122 offset:14592
	s_waitcnt lgkmcnt(12)
	v_mul_f32_e32 v36, v28, v10
	v_fmac_f32_e32 v36, v29, v11
	v_fmac_f32_e32 v36, v30, v12
	v_fmac_f32_e32 v36, v31, v13
	v_mul_f32_e32 v10, v64, v10
	v_mul_f32_e32 v11, v64, v11
	v_add_f32_dpp v36, v36, v36 quad_perm:[1,0,3,2] row_mask:0xf bank_mask:0xf bound_ctrl:1
	v_mul_f32_e32 v12, v64, v12
	v_mul_f32_e32 v13, v64, v13
	v_add_f32_dpp v36, v36, v36 quad_perm:[2,3,0,1] row_mask:0xf bank_mask:0xf bound_ctrl:1
	s_waitcnt lgkmcnt(8)
	v_add_f32_e32 v140, v140, v158
	v_add_f32_dpp v36, v36, v36 row_half_mirror row_mask:0xf bank_mask:0xf bound_ctrl:1
	v_add_f32_e32 v141, v141, v159
	v_add_f32_e32 v142, v142, v160
	v_add_f32_dpp v36, v36, v36 row_mirror row_mask:0xf bank_mask:0xf bound_ctrl:1
	v_add_f32_e32 v143, v143, v161
	v_fma_f32 v19, -v63, v36, v62
	v_fmac_f32_e32 v10, v28, v19
	v_fmac_f32_e32 v11, v29, v19
	v_fmac_f32_e32 v12, v30, v19
	v_fmac_f32_e32 v13, v31, v19
	v_mul_f32_e32 v122, v46, v10
	v_fmac_f32_e32 v122, v47, v11
	v_fmac_f32_e32 v122, v48, v12
	v_fmac_f32_e32 v122, v49, v13
	ds_write_b32 v133, v122 offset:14848
	ds_read_b128 v[24:27], v0 offset:4864
	ds_read_b128 v[42:45], v0 offset:6912
	ds_read_b128 v[58:61], v1 offset:8768
	v_add_f32_e32 v154, v154, v162
	v_add_f32_e32 v155, v155, v163
	v_add_f32_e32 v156, v156, v164
	v_add_f32_e32 v157, v157, v165
	v_add_f32_e32 v140, v140, v154
	v_add_f32_e32 v141, v141, v155
	v_add_f32_e32 v142, v142, v156
	v_add_f32_e32 v143, v143, v157
	v_add_f32_e32 v140, v140, v141
	v_add_f32_e32 v142, v142, v143
	v_add_f32_e32 v140, v140, v142
	v_cvt_pk_bf16_f32 v18, v140, v140
	ds_write_b16 v131, v18 offset:17664
	s_waitcnt lgkmcnt(9)
	v_mul_f32_e32 v36, v32, v10
	v_fmac_f32_e32 v36, v33, v11
	v_fmac_f32_e32 v36, v34, v12
	v_fmac_f32_e32 v36, v35, v13
	v_mul_f32_e32 v10, v68, v10
	v_mul_f32_e32 v11, v68, v11
	v_add_f32_dpp v36, v36, v36 quad_perm:[1,0,3,2] row_mask:0xf bank_mask:0xf bound_ctrl:1
	v_mul_f32_e32 v12, v68, v12
	v_mul_f32_e32 v13, v68, v13
	v_add_f32_dpp v36, v36, v36 quad_perm:[2,3,0,1] row_mask:0xf bank_mask:0xf bound_ctrl:1
	ds_read_b128 v[28:31], v0 offset:5120
	ds_read_b128 v[46:49], v0 offset:7168
	v_add_f32_dpp v36, v36, v36 row_half_mirror row_mask:0xf bank_mask:0xf bound_ctrl:1
	ds_read_b128 v[62:65], v1 offset:8832
	s_nop 0
	v_add_f32_dpp v36, v36, v36 row_mirror row_mask:0xf bank_mask:0xf bound_ctrl:1
	s_nop 0
	v_fma_f32 v19, -v67, v36, v66
	v_fmac_f32_e32 v10, v32, v19
	v_fmac_f32_e32 v11, v33, v19
	v_fmac_f32_e32 v12, v34, v19
	v_fmac_f32_e32 v13, v35, v19
	v_mul_f32_e32 v122, v50, v10
	v_fmac_f32_e32 v122, v51, v11
	v_fmac_f32_e32 v122, v52, v12
	v_fmac_f32_e32 v122, v53, v13
	ds_write_b32 v133, v122 offset:15104
	s_waitcnt lgkmcnt(10)
	v_mul_f32_e32 v36, v20, v10
	v_fmac_f32_e32 v36, v21, v11
	v_fmac_f32_e32 v36, v22, v12
	v_fmac_f32_e32 v36, v23, v13
	v_mul_f32_e32 v10, v56, v10
	v_mul_f32_e32 v11, v56, v11
	v_add_f32_dpp v36, v36, v36 quad_perm:[1,0,3,2] row_mask:0xf bank_mask:0xf bound_ctrl:1
	v_mul_f32_e32 v12, v56, v12
	v_mul_f32_e32 v13, v56, v13
	v_add_f32_dpp v36, v36, v36 quad_perm:[2,3,0,1] row_mask:0xf bank_mask:0xf bound_ctrl:1
	s_waitcnt vmcnt(14)
	v_lshlrev_b32_e32 v118, 16, v74
	v_add_f32_dpp v36, v36, v36 row_half_mirror row_mask:0xf bank_mask:0xf bound_ctrl:1
	v_and_b32_e32 v119, 0xffff0000, v74
	v_lshlrev_b32_e32 v120, 16, v75
	v_add_f32_dpp v36, v36, v36 row_mirror row_mask:0xf bank_mask:0xf bound_ctrl:1
	v_and_b32_e32 v121, 0xffff0000, v75
	v_fma_f32 v19, -v55, v36, v54
	v_fmac_f32_e32 v10, v20, v19
	v_fmac_f32_e32 v11, v21, v19
	v_fmac_f32_e32 v12, v22, v19
	v_fmac_f32_e32 v13, v23, v19
	v_mul_f32_e32 v122, v38, v10
	v_fmac_f32_e32 v122, v39, v11
	v_fmac_f32_e32 v122, v40, v12
	v_fmac_f32_e32 v122, v41, v13
	ds_write_b32 v133, v122 offset:15360
	ds_read_b128 v[32:35], v0 offset:5376
	ds_read_b128 v[50:53], v0 offset:7424
	ds_read_b128 v[66:69], v1 offset:8896
	ds_write_b128 v2, v[118:121] offset:0
	v_lshlrev_b32_e32 v124, 16, v76
	v_and_b32_e32 v125, 0xffff0000, v76
	s_waitcnt lgkmcnt(10)
	v_mul_f32_e32 v36, v24, v10
	v_fmac_f32_e32 v36, v25, v11
	v_fmac_f32_e32 v36, v26, v12
	v_fmac_f32_e32 v36, v27, v13
	v_mul_f32_e32 v10, v60, v10
	v_mul_f32_e32 v11, v60, v11
	v_add_f32_dpp v36, v36, v36 quad_perm:[1,0,3,2] row_mask:0xf bank_mask:0xf bound_ctrl:1
	v_mul_f32_e32 v12, v60, v12
	v_mul_f32_e32 v13, v60, v13
	v_add_f32_dpp v36, v36, v36 quad_perm:[2,3,0,1] row_mask:0xf bank_mask:0xf bound_ctrl:1
	v_lshlrev_b32_e32 v126, 16, v77
	v_and_b32_e32 v127, 0xffff0000, v77
	v_add_f32_dpp v36, v36, v36 row_half_mirror row_mask:0xf bank_mask:0xf bound_ctrl:1
	ds_write_b128 v2, v[124:127] offset:16
	v_lshlrev_b32_e32 v118, 16, v70
	v_add_f32_dpp v36, v36, v36 row_mirror row_mask:0xf bank_mask:0xf bound_ctrl:1
	v_and_b32_e32 v119, 0xffff0000, v70
	v_fma_f32 v19, -v59, v36, v58
	v_fmac_f32_e32 v10, v24, v19
	v_fmac_f32_e32 v11, v25, v19
	v_fmac_f32_e32 v12, v26, v19
	v_fmac_f32_e32 v13, v27, v19
	v_mul_f32_e32 v122, v42, v10
	v_fmac_f32_e32 v122, v43, v11
	v_fmac_f32_e32 v122, v44, v12
	v_fmac_f32_e32 v122, v45, v13
	ds_write_b32 v133, v122 offset:15616
	ds_read_b128 v[20:23], v0 offset:5632
	ds_read_b128 v[38:41], v0 offset:7680
	ds_read_b128 v[54:57], v1 offset:8960
	v_lshlrev_b32_e32 v120, 16, v71
	v_and_b32_e32 v121, 0xffff0000, v71
	ds_write_b128 v2, v[118:121] offset:2048
	s_waitcnt lgkmcnt(12)
	v_mul_f32_e32 v36, v28, v10
	v_fmac_f32_e32 v36, v29, v11
	v_fmac_f32_e32 v36, v30, v12
	v_fmac_f32_e32 v36, v31, v13
	v_mul_f32_e32 v10, v64, v10
	v_mul_f32_e32 v11, v64, v11
	v_add_f32_dpp v36, v36, v36 quad_perm:[1,0,3,2] row_mask:0xf bank_mask:0xf bound_ctrl:1
	v_mul_f32_e32 v12, v64, v12
	v_mul_f32_e32 v13, v64, v13
	v_add_f32_dpp v36, v36, v36 quad_perm:[2,3,0,1] row_mask:0xf bank_mask:0xf bound_ctrl:1
	v_lshlrev_b32_e32 v124, 16, v72
	v_and_b32_e32 v125, 0xffff0000, v72
	v_add_f32_dpp v36, v36, v36 row_half_mirror row_mask:0xf bank_mask:0xf bound_ctrl:1
	v_lshlrev_b32_e32 v126, 16, v73
	v_and_b32_e32 v127, 0xffff0000, v73
	v_add_f32_dpp v36, v36, v36 row_mirror row_mask:0xf bank_mask:0xf bound_ctrl:1
	ds_write_b128 v2, v[124:127] offset:2064
	v_fma_f32 v19, -v63, v36, v62
	v_fmac_f32_e32 v10, v28, v19
	v_fmac_f32_e32 v11, v29, v19
	v_fmac_f32_e32 v12, v30, v19
	v_fmac_f32_e32 v13, v31, v19
	v_mul_f32_e32 v122, v46, v10
	v_fmac_f32_e32 v122, v47, v11
	v_fmac_f32_e32 v122, v48, v12
	v_fmac_f32_e32 v122, v49, v13
	ds_write_b32 v133, v122 offset:15872
	ds_read_b128 v[24:27], v0 offset:5888
	ds_read_b128 v[42:45], v0 offset:7936
	ds_read_b128 v[58:61], v1 offset:9024
	s_waitcnt vmcnt(12)
	v_mov_b32_dpp v80, v79 quad_perm:[1,1,1,1] row_mask:0xf bank_mask:0xf
	v_mov_b32_dpp v79, v79 quad_perm:[0,0,0,0] row_mask:0xf bank_mask:0xf
	s_waitcnt lgkmcnt(12)
	v_mul_f32_e32 v36, v32, v10
	v_fmac_f32_e32 v36, v33, v11
	v_fmac_f32_e32 v36, v34, v12
	v_fmac_f32_e32 v36, v35, v13
	v_mul_f32_e32 v10, v68, v10
	v_mul_f32_e32 v11, v68, v11
	v_add_f32_dpp v36, v36, v36 quad_perm:[1,0,3,2] row_mask:0xf bank_mask:0xf bound_ctrl:1
	v_mul_f32_e32 v12, v68, v12
	v_mul_f32_e32 v13, v68, v13
	v_add_f32_dpp v36, v36, v36 quad_perm:[2,3,0,1] row_mask:0xf bank_mask:0xf bound_ctrl:1
	v_lshlrev_b32_e32 v78, 16, v78
	v_mul_f32_e32 v78, v79, v78
	v_add_f32_dpp v36, v36, v36 row_half_mirror row_mask:0xf bank_mask:0xf bound_ctrl:1
	v_mul_f32_e32 v79, v79, v80
	s_nop 0
	v_add_f32_dpp v36, v36, v36 row_mirror row_mask:0xf bank_mask:0xf bound_ctrl:1
	ds_write_b128 v4, v[78:81] offset:4096
	v_fma_f32 v19, -v67, v36, v66
	v_fmac_f32_e32 v10, v32, v19
	v_fmac_f32_e32 v11, v33, v19
	v_fmac_f32_e32 v12, v34, v19
	v_fmac_f32_e32 v13, v35, v19
	v_mul_f32_e32 v122, v50, v10
	v_fmac_f32_e32 v122, v51, v11
	v_fmac_f32_e32 v122, v52, v12
	v_fmac_f32_e32 v122, v53, v13
	ds_write_b32 v133, v122 offset:16128
	ds_read_b128 v[28:31], v0 offset:6144
	ds_read_b128 v[46:49], v0 offset:8192
	ds_read_b128 v[62:65], v1 offset:9088
	s_waitcnt lgkmcnt(11)
	v_mul_f32_e32 v36, v20, v10
	v_fmac_f32_e32 v36, v21, v11
	v_fmac_f32_e32 v36, v22, v12
	v_fmac_f32_e32 v36, v23, v13
	v_mul_f32_e32 v10, v56, v10
	v_mul_f32_e32 v11, v56, v11
	v_add_f32_dpp v36, v36, v36 quad_perm:[1,0,3,2] row_mask:0xf bank_mask:0xf bound_ctrl:1
	v_mul_f32_e32 v12, v56, v12
	v_mul_f32_e32 v13, v56, v13
	v_add_f32_dpp v36, v36, v36 quad_perm:[2,3,0,1] row_mask:0xf bank_mask:0xf bound_ctrl:1
	global_load_dwordx4 v[70:73], v5, s[94:95]
	global_load_dwordx4 v[74:77], v5, s[94:95] offset:512
	global_load_ushort v78, v6, s[94:95]
	global_load_dword v79, v8, s[94:95]
	v_add_u32_e32 v5, 0x6800, v5
	v_add_u32_e32 v6, 0x6800, v6
	v_add_u32_e32 v8, 0x3180, v8
	ds_read_b128 v[32:35], v0 offset:6400
	v_add_f32_dpp v36, v36, v36 row_half_mirror row_mask:0xf bank_mask:0xf bound_ctrl:1
	ds_read_b128 v[50:53], v0 offset:8448
	ds_read_b128 v[66:69], v1 offset:9152
	v_add_f32_dpp v36, v36, v36 row_mirror row_mask:0xf bank_mask:0xf bound_ctrl:1
	s_nop 0
	v_fma_f32 v19, -v55, v36, v54
	v_fmac_f32_e32 v10, v20, v19
	v_fmac_f32_e32 v11, v21, v19
	v_fmac_f32_e32 v12, v22, v19
	v_fmac_f32_e32 v13, v23, v19
	v_mul_f32_e32 v122, v38, v10
	v_fmac_f32_e32 v122, v39, v11
	v_fmac_f32_e32 v122, v40, v12
	v_fmac_f32_e32 v122, v41, v13
	ds_write_b32 v133, v122 offset:16384
	s_waitcnt lgkmcnt(9)
	v_mul_f32_e32 v36, v24, v10
	v_fmac_f32_e32 v36, v25, v11
	v_fmac_f32_e32 v36, v26, v12
	v_fmac_f32_e32 v36, v27, v13
	v_mul_f32_e32 v10, v60, v10
	v_mul_f32_e32 v11, v60, v11
	v_add_f32_dpp v36, v36, v36 quad_perm:[1,0,3,2] row_mask:0xf bank_mask:0xf bound_ctrl:1
	v_mul_f32_e32 v12, v60, v12
	v_mul_f32_e32 v13, v60, v13
	v_add_f32_dpp v36, v36, v36 quad_perm:[2,3,0,1] row_mask:0xf bank_mask:0xf bound_ctrl:1
	ds_read_b128 v[20:23], v0 offset:0
	ds_read_b128 v[38:41], v0 offset:2048
	v_add_f32_dpp v36, v36, v36 row_half_mirror row_mask:0xf bank_mask:0xf bound_ctrl:1
	ds_read_b128 v[54:57], v1 offset:4096
	s_nop 0
	v_add_f32_dpp v36, v36, v36 row_mirror row_mask:0xf bank_mask:0xf bound_ctrl:1
	s_nop 0
	v_fma_f32 v19, -v59, v36, v58
	v_fmac_f32_e32 v10, v24, v19
	v_fmac_f32_e32 v11, v25, v19
	v_fmac_f32_e32 v12, v26, v19
	v_fmac_f32_e32 v13, v27, v19
	v_mul_f32_e32 v122, v42, v10
	v_fmac_f32_e32 v122, v43, v11
	v_fmac_f32_e32 v122, v44, v12
	v_fmac_f32_e32 v122, v45, v13
	ds_write_b32 v133, v122 offset:16640
	s_waitcnt lgkmcnt(8)
	v_mul_f32_e32 v36, v28, v10
	v_fmac_f32_e32 v36, v29, v11
	v_fmac_f32_e32 v36, v30, v12
	v_fmac_f32_e32 v36, v31, v13
	v_mul_f32_e32 v10, v64, v10
	v_mul_f32_e32 v11, v64, v11
	v_add_f32_dpp v36, v36, v36 quad_perm:[1,0,3,2] row_mask:0xf bank_mask:0xf bound_ctrl:1
	v_mul_f32_e32 v12, v64, v12
	v_mul_f32_e32 v13, v64, v13
	v_add_f32_dpp v36, v36, v36 quad_perm:[2,3,0,1] row_mask:0xf bank_mask:0xf bound_ctrl:1
	ds_read_b128 v[24:27], v0 offset:256
	ds_read_b128 v[42:45], v0 offset:2304
	v_add_f32_dpp v36, v36, v36 row_half_mirror row_mask:0xf bank_mask:0xf bound_ctrl:1
	ds_read_b128 v[58:61], v1 offset:4160
	s_nop 0
	v_add_f32_dpp v36, v36, v36 row_mirror row_mask:0xf bank_mask:0xf bound_ctrl:1
	s_nop 0
	v_fma_f32 v19, -v63, v36, v62
	v_fmac_f32_e32 v10, v28, v19
	v_fmac_f32_e32 v11, v29, v19
	v_fmac_f32_e32 v12, v30, v19
	v_fmac_f32_e32 v13, v31, v19
	v_mul_f32_e32 v122, v46, v10
	v_fmac_f32_e32 v122, v47, v11
	v_fmac_f32_e32 v122, v48, v12
	v_fmac_f32_e32 v122, v49, v13
	ds_write_b32 v133, v122 offset:16896
	s_waitcnt lgkmcnt(9)
	v_mul_f32_e32 v36, v32, v10
	v_fmac_f32_e32 v36, v33, v11
	v_fmac_f32_e32 v36, v34, v12
	v_fmac_f32_e32 v36, v35, v13
	v_mul_f32_e32 v10, v68, v10
	v_mul_f32_e32 v11, v68, v11
	v_add_f32_dpp v36, v36, v36 quad_perm:[1,0,3,2] row_mask:0xf bank_mask:0xf bound_ctrl:1
	v_mul_f32_e32 v12, v68, v12
	v_mul_f32_e32 v13, v68, v13
	v_add_f32_dpp v36, v36, v36 quad_perm:[2,3,0,1] row_mask:0xf bank_mask:0xf bound_ctrl:1
	ds_read_b128 v[28:31], v0 offset:512
	ds_read_b128 v[46:49], v0 offset:2560
	v_add_f32_dpp v36, v36, v36 row_half_mirror row_mask:0xf bank_mask:0xf bound_ctrl:1
	ds_read_b128 v[62:65], v1 offset:4224
	s_nop 0
	v_add_f32_dpp v36, v36, v36 row_mirror row_mask:0xf bank_mask:0xf bound_ctrl:1
	s_nop 0
	v_fma_f32 v19, -v67, v36, v66
	v_fmac_f32_e32 v10, v32, v19
	v_fmac_f32_e32 v11, v33, v19
	v_fmac_f32_e32 v12, v34, v19
	v_fmac_f32_e32 v13, v35, v19
	v_mul_f32_e32 v122, v50, v10
	v_fmac_f32_e32 v122, v51, v11
	v_fmac_f32_e32 v122, v52, v12
	v_fmac_f32_e32 v122, v53, v13
	ds_write_b32 v133, v122 offset:17152
	s_sub_u32 s12, s12, 1
	s_cmp_lg_u32 s12, 0
	s_cbranch_scc1 .Lls3_16_loop
	ds_read_b128 v[140:143], v136 offset:13312
	ds_read_b128 v[154:157], v137 offset:13312
	ds_read_b128 v[158:161], v138 offset:13312
	ds_read_b128 v[162:165], v139 offset:13312
	s_waitcnt lgkmcnt(0)
	v_add_f32_e32 v140, v140, v158
	v_add_f32_e32 v141, v141, v159
	v_add_f32_e32 v142, v142, v160
	v_add_f32_e32 v143, v143, v161
	v_add_f32_e32 v154, v154, v162
	v_add_f32_e32 v155, v155, v163
	v_add_f32_e32 v156, v156, v164
	v_add_f32_e32 v157, v157, v165
	v_add_f32_e32 v140, v140, v154
	v_add_f32_e32 v141, v141, v155
	v_add_f32_e32 v142, v142, v156
	v_add_f32_e32 v143, v143, v157
	v_add_f32_e32 v140, v140, v141
	v_add_f32_e32 v142, v142, v143
	v_add_f32_e32 v140, v140, v142
	v_cvt_pk_bf16_f32 v18, v140, v140
	ds_write_b16 v131, v18 offset:17792
	s_waitcnt lgkmcnt(0)
	ds_read_b64 v[134:135], v132 offset:17664
	s_waitcnt lgkmcnt(0)
	global_store_dwordx2 v7, v[134:135], s[94:95]
	v_add_u32_e32 v7, 0x20000, v7
	s_nop 0
	ds_read_b64 v[134:135], v132 offset:18176
	s_waitcnt lgkmcnt(0)
	global_store_dwordx2 v7, v[134:135], s[94:95]
	v_add_u32_e32 v7, 0x20000, v7
	s_nop 0
	ds_read_b64 v[134:135], v132 offset:18688
	s_waitcnt lgkmcnt(0)
	global_store_dwordx2 v7, v[134:135], s[94:95]
	v_add_u32_e32 v7, 0x20000, v7
	s_nop 0
	ds_read_b64 v[134:135], v132 offset:19200
	s_waitcnt lgkmcnt(0)
	global_store_dwordx2 v7, v[134:135], s[94:95]
	v_add_u32_e32 v7, 0x20000, v7
	s_nop 0
	ds_read_b64 v[134:135], v132 offset:19712
	s_waitcnt lgkmcnt(0)
	global_store_dwordx2 v7, v[134:135], s[94:95]
	v_add_u32_e32 v7, 0x20000, v7
	s_nop 0
	ds_read_b64 v[134:135], v132 offset:20224
	s_waitcnt lgkmcnt(0)
	global_store_dwordx2 v7, v[134:135], s[94:95]
	v_add_u32_e32 v7, 0x20000, v7
	s_nop 0
	ds_read_b64 v[134:135], v132 offset:20736
	s_waitcnt lgkmcnt(0)
	global_store_dwordx2 v7, v[134:135], s[94:95]
	v_add_u32_e32 v7, 0x20000, v7
	s_nop 0
	ds_read_b64 v[134:135], v132 offset:21248
	s_waitcnt lgkmcnt(0)
	global_store_dwordx2 v7, v[134:135], s[94:95]
	v_add_u32_e32 v7, 0x20000, v7
	s_nop 0
	global_store_dword v130, v10, s[26:27] offset:0
	global_store_dword v130, v11, s[26:27] offset:256
	global_store_dword v130, v12, s[26:27] offset:512
	global_store_dword v130, v13, s[26:27] offset:768
	s_waitcnt vmcnt(0) lgkmcnt(0)
	s_setprio 0
	s_branch .Lls_done
.Lls0_8_entry:
	v_and_b32_e32 v98, 63, v196
	v_and_b32_e32 v99, 7, v98
	v_lshrrev_b32_e32 v100, 3, v98
	s_min_u32 s29, s0, 4
	s_mul_i32 s29, s29, 0x5600
	v_and_b32_e32 v101, 3, v99
	v_cmp_eq_u32_e64 s[6:7], 1, v101
	v_cmp_eq_u32_e64 s[8:9], 2, v101
	v_cmp_eq_u32_e64 s[10:11], 3, v101
	v_lshl_add_u32 v0, v99, 5, s29
	v_lshl_add_u32 v1, v100, 2, s29
	s_lshl_b32 s37, s16, 11
	v_lshrrev_b32_e32 v99, 3, v98
	v_and_b32_e32 v100, 7, v98
	v_add_u32_e32 v101, s37, v99
	s_lshl_b32 s21, s17, 7
	s_add_u32 s21, s21, 0x10800000
	v_mul_u32_u24_e32 v5, 0xd00, v101
	v_lshl_add_u32 v5, v100, 4, v5
	v_add_u32_e32 v5, s21, v5
	v_lshlrev_b32_e32 v2, 8, v99
	v_lshl_add_u32 v2, v100, 5, v2
	v_add_u32_e32 v2, s29, v2
	v_lshrrev_b32_e32 v100, 3, v98
	v_and_b32_e32 v99, 7, v98
	v_add_u32_e32 v101, s37, v100
	s_lshl_b32 s22, s14, 3
	s_lshl_b32 s21, s17, 6
	s_add_u32 s21, s21, s22
	s_lshl_b32 s44, s21, 1
	s_add_u32 s44, s44, 0x8400400
	v_lshlrev_b32_e32 v6, 13, v101
	v_lshlrev_b32_e32 v4, 5, v100
	v_lshl_add_u32 v4, v99, 2, v4
	v_lshl_add_u32 v6, v99, 1, v6
	v_add_u32_e32 v6, s44, v6
	v_add_u32_e32 v4, s29, v4
	v_and_b32_e32 v99, 7, v98
	v_lshrrev_b32_e32 v100, 3, v98
	v_add_u32_e32 v101, s37, v98
	v_lshlrev_b32_e32 v7, 11, v101
	s_lshl_b32 s44, s21, 1
	s_add_u32 s44, s44, 0x6300000
	v_add_u32_e32 v7, s44, v7
	s_lshl_b32 s44, s28, 3
	s_add_u32 s44, s44, s16
	s_lshl_b32 s44, s44, 2
	s_add_u32 s44, s44, s17
	s_mul_i32 s44, s44, 0x4000
	s_add_u32 s44, s44, 0x4200000
	s_lshl_b32 s24, s22, 2
	s_add_u32 s44, s44, s24
	v_lshlrev_b32_e32 v111, 11, v99
	v_lshl_add_u32 v111, v100, 2, v111
	v_add_u32_e32 v111, s44, v111
	v_readlane_b32 s26, v253, 29
	v_readlane_b32 s27, v253, 30
	v_lshlrev_b32_e32 v112, 4, v99
	v_lshl_add_u32 v112, v100, 1, v112
	v_add_u32_e32 v112, s29, v112
	v_lshl_add_u32 v113, v98, 4, s29
	v_lshl_add_u32 v118, v98, 2, s29
	v_lshl_add_u32 v112, v98, 1, s29
	v_subrev_u32_e32 v112, 0x200, v112
	v_lshrrev_b32_e32 v99, 3, v98
	v_and_b32_e32 v100, 7, v98
	v_lshlrev_b32_e32 v101, 8, v99
	v_lshl_add_u32 v101, v100, 5, v101
	v_add_u32_e32 v101, s29, v101
	v_bfe_u32 v99, v99, 1, 1
	v_xor_b32_e32 v100, 0, v99
	v_lshl_add_u32 v119, v100, 4, v101
	v_xor_b32_e32 v100, 1, v99
	v_lshl_add_u32 v120, v100, 4, v101
	s_lshr_b32 s44, 0x80000, s17
	s_sub_u32 s44, 0x3f800000, s44
	s_mov_b32 s45, s44
	v_mov_b32_e32 v98, s45
	v_log_f32_e32 v98, v98
	v_lshrrev_b32_e32 v99, 3, v196
	v_and_b32_e32 v99, 7, v99
	v_add_u32_e32 v100, 1, v99
	v_cvt_f32_u32_e32 v100, v100
	v_mul_f32_e32 v100, v98, v100
	v_exp_f32_e32 v107, v100
	v_sub_f32_e32 v101, 0, v100
	v_exp_f32_e32 v103, v101
	v_add_u32_e32 v100, 9, v99
	v_cvt_f32_u32_e32 v100, v100
	v_mul_f32_e32 v100, v98, v100
	v_exp_f32_e32 v108, v100
	v_sub_f32_e32 v101, 0, v100
	v_exp_f32_e32 v104, v101
	v_add_u32_e32 v100, 17, v99
	v_cvt_f32_u32_e32 v100, v100
	v_mul_f32_e32 v100, v98, v100
	v_exp_f32_e32 v109, v100
	v_sub_f32_e32 v101, 0, v100
	v_exp_f32_e32 v105, v101
	v_add_u32_e32 v100, 25, v99
	v_cvt_f32_u32_e32 v100, v100
	v_mul_f32_e32 v100, v98, v100
	v_exp_f32_e32 v110, v100
	v_sub_f32_e32 v101, 0, v100
	v_exp_f32_e32 v106, v101
	v_mul_f32_e32 v100, 0x42000000, v98
	v_exp_f32_e32 v100, v100
	s_nop 1
	v_readfirstlane_b32 s44, v100
	v_mov_b32_e32 v8, 0
	v_mov_b32_e32 v9, 0
	v_mov_b32_e32 v10, 0
	v_mov_b32_e32 v11, 0
	v_mov_b32_e32 v12, 0
	v_mov_b32_e32 v13, 0
	v_mov_b32_e32 v14, 0
	v_mov_b32_e32 v15, 0
	v_mov_b32_e32 v16, 0
	v_mov_b32_e32 v17, 0
	v_mov_b32_e32 v18, 0
	v_mov_b32_e32 v19, 0
	v_mov_b32_e32 v36, 0
	v_mov_b32_e32 v102, 0
	s_setprio 2
	s_movk_i32 s12, 64
	s_nop 0
	global_load_dwordx4 v[62:65], v5, s[94:95]
	global_load_dwordx4 v[66:69], v5, s[94:95] offset:512
	global_load_ushort v31, v6, s[94:95]
	v_add_u32_e32 v5, 0x6800, v5
	v_add_u32_e32 v6, 0x10000, v6
	s_waitcnt vmcnt(0)
	s_waitcnt vmcnt(1)
	v_lshlrev_b32_e32 v94, 16, v66
	v_and_b32_e32 v95, 0xffff0000, v66
	v_lshlrev_b32_e32 v96, 16, v67
	v_and_b32_e32 v97, 0xffff0000, v67
	ds_write_b128 v2, v[94:97] offset:0
	v_lshlrev_b32_e32 v98, 16, v68
	v_and_b32_e32 v99, 0xffff0000, v68
	v_lshlrev_b32_e32 v100, 16, v69
	v_and_b32_e32 v101, 0xffff0000, v69
	ds_write_b128 v2, v[98:101] offset:16
	v_lshlrev_b32_e32 v94, 16, v62
	v_and_b32_e32 v95, 0xffff0000, v62
	v_lshlrev_b32_e32 v96, 16, v63
	v_and_b32_e32 v97, 0xffff0000, v63
	ds_write_b128 v2, v[94:97] offset:2048
	v_lshlrev_b32_e32 v98, 16, v64
	v_and_b32_e32 v99, 0xffff0000, v64
	v_lshlrev_b32_e32 v100, 16, v65
	v_and_b32_e32 v101, 0xffff0000, v65
	ds_write_b128 v2, v[98:101] offset:2064
	s_waitcnt vmcnt(0)
	v_lshlrev_b32_e32 v31, 16, v31
	v_mul_f32_e32 v31, v103, v31
	s_nop 0
	ds_write_b32 v4, v31 offset:4096
	global_load_dwordx4 v[70:73], v5, s[94:95]
	global_load_dwordx4 v[74:77], v5, s[94:95] offset:512
	global_load_ushort v33, v6, s[94:95]
	v_add_u32_e32 v5, 0x6800, v5
	v_add_u32_e32 v6, 0x10000, v6
	global_load_dwordx4 v[78:81], v5, s[94:95]
	global_load_dwordx4 v[82:85], v5, s[94:95] offset:512
	global_load_ushort v34, v6, s[94:95]
	v_add_u32_e32 v5, 0x6800, v5
	v_add_u32_e32 v6, 0x10000, v6
	global_load_dwordx4 v[86:89], v5, s[94:95]
	global_load_dwordx4 v[90:93], v5, s[94:95] offset:512
	global_load_ushort v35, v6, s[94:95]
	v_add_u32_e32 v5, 0x6800, v5
	v_add_u32_e32 v6, 0x10000, v6
	global_load_dwordx4 v[62:65], v5, s[94:95]
	global_load_dwordx4 v[66:69], v5, s[94:95] offset:512
	global_load_ushort v31, v6, s[94:95]
	v_add_u32_e32 v5, 0x6800, v5
	v_add_u32_e32 v6, 0x10000, v6
	ds_read_b128 v[22:25], v0 offset:0
	ds_read_b128 v[26:29], v0 offset:16
	ds_read_b128 v[46:49], v0 offset:2048
	ds_read_b128 v[50:53], v0 offset:2064
	ds_read_b32 v30, v1 offset:4096
.Lls0_8_loop:
	s_waitcnt lgkmcnt(0)
	ds_read_b128 v[38:41], v0 offset:256
	ds_read_b128 v[42:45], v0 offset:272
	ds_read_b128 v[54:57], v0 offset:2304
	ds_read_b128 v[58:61], v0 offset:2320
	ds_read_b32 v32, v1 offset:4128
	v_fmac_f32_e32 v8, v22, v30
	v_fmac_f32_e32 v9, v23, v30
	v_mul_f32_e32 v36, v46, v8
	s_waitcnt vmcnt(10)
	v_fmac_f32_e32 v10, v24, v30
	v_fmac_f32_e32 v36, v47, v9
	v_fmac_f32_e32 v11, v25, v30
	v_lshlrev_b32_e32 v94, 16, v74
	v_fmac_f32_e32 v36, v48, v10
	v_fmac_f32_e32 v12, v26, v30
	v_fmac_f32_e32 v36, v49, v11
	v_and_b32_e32 v95, 0xffff0000, v74
	v_fmac_f32_e32 v13, v27, v30
	v_fmac_f32_e32 v36, v50, v12
	v_fmac_f32_e32 v14, v28, v30
	v_lshlrev_b32_e32 v96, 16, v75
	v_fmac_f32_e32 v36, v51, v13
	v_fmac_f32_e32 v15, v29, v30
	v_fmac_f32_e32 v36, v52, v14
	v_and_b32_e32 v97, 0xffff0000, v75
	v_fmac_f32_e32 v36, v53, v15
	ds_write_b32 v118, v36 offset:8704
	ds_write_b128 v2, v[94:97] offset:4352
	v_lshlrev_b32_e32 v98, 16, v76
	s_waitcnt lgkmcnt(2)
	ds_read_b128 v[22:25], v0 offset:512
	ds_read_b128 v[26:29], v0 offset:528
	ds_read_b128 v[46:49], v0 offset:2560
	ds_read_b128 v[50:53], v0 offset:2576
	ds_read_b32 v30, v1 offset:4160
	v_fmac_f32_e32 v8, v38, v32
	v_fmac_f32_e32 v9, v39, v32
	v_mul_f32_e32 v102, v54, v8
	v_and_b32_e32 v99, 0xffff0000, v76
	v_fmac_f32_e32 v10, v40, v32
	v_fmac_f32_e32 v102, v55, v9
	v_fmac_f32_e32 v11, v41, v32
	v_lshlrev_b32_e32 v100, 16, v77
	v_fmac_f32_e32 v102, v56, v10
	v_fmac_f32_e32 v12, v42, v32
	v_fmac_f32_e32 v102, v57, v11
	v_and_b32_e32 v101, 0xffff0000, v77
	v_fmac_f32_e32 v13, v43, v32
	v_fmac_f32_e32 v102, v58, v12
	v_fmac_f32_e32 v14, v44, v32
	ds_write_b128 v2, v[98:101] offset:4368
	v_fmac_f32_e32 v102, v59, v13
	v_fmac_f32_e32 v15, v45, v32
	v_fmac_f32_e32 v102, v60, v14
	v_lshlrev_b32_e32 v94, 16, v70
	v_fmac_f32_e32 v102, v61, v15
	ds_write_b32 v118, v102 offset:8960
	v_and_b32_e32 v95, 0xffff0000, v70
	v_lshlrev_b32_e32 v96, 16, v71
	s_waitcnt lgkmcnt(2)
	ds_read_b128 v[38:41], v0 offset:768
	ds_read_b128 v[42:45], v0 offset:784
	ds_read_b128 v[54:57], v0 offset:2816
	ds_read_b128 v[58:61], v0 offset:2832
	ds_read_b32 v32, v1 offset:4192
	v_fmac_f32_e32 v8, v22, v30
	v_fmac_f32_e32 v9, v23, v30
	v_mul_f32_e32 v36, v46, v8
	v_and_b32_e32 v97, 0xffff0000, v71
	v_fmac_f32_e32 v10, v24, v30
	v_fmac_f32_e32 v36, v47, v9
	v_fmac_f32_e32 v11, v25, v30
	ds_write_b128 v2, v[94:97] offset:6400
	v_fmac_f32_e32 v36, v48, v10
	v_fmac_f32_e32 v12, v26, v30
	v_fmac_f32_e32 v36, v49, v11
	v_lshlrev_b32_e32 v98, 16, v72
	v_fmac_f32_e32 v13, v27, v30
	v_fmac_f32_e32 v36, v50, v12
	v_fmac_f32_e32 v14, v28, v30
	v_and_b32_e32 v99, 0xffff0000, v72
	v_fmac_f32_e32 v36, v51, v13
	v_fmac_f32_e32 v15, v29, v30
	v_fmac_f32_e32 v36, v52, v14
	v_lshlrev_b32_e32 v100, 16, v73
	v_fmac_f32_e32 v36, v53, v15
	ds_write_b32 v118, v36 offset:9216
	v_and_b32_e32 v101, 0xffff0000, v73
	ds_write_b128 v2, v[98:101] offset:6416
	s_waitcnt lgkmcnt(3)
	ds_read_b128 v[22:25], v0 offset:1024
	ds_read_b128 v[26:29], v0 offset:1040
	ds_read_b128 v[46:49], v0 offset:3072
	ds_read_b128 v[50:53], v0 offset:3088
	ds_read_b32 v30, v1 offset:4224
	v_fmac_f32_e32 v8, v38, v32
	v_fmac_f32_e32 v9, v39, v32
	v_mul_f32_e32 v102, v54, v8
	s_waitcnt vmcnt(9)
	v_fmac_f32_e32 v10, v40, v32
	v_fmac_f32_e32 v102, v55, v9
	v_fmac_f32_e32 v11, v41, v32
	v_lshlrev_b32_e32 v33, 16, v33
	v_fmac_f32_e32 v102, v56, v10
	v_fmac_f32_e32 v12, v42, v32
	v_fmac_f32_e32 v102, v57, v11
	v_mul_f32_e32 v33, v104, v33
	v_fmac_f32_e32 v13, v43, v32
	v_fmac_f32_e32 v102, v58, v12
	v_fmac_f32_e32 v14, v44, v32
	s_nop 0
	v_fmac_f32_e32 v102, v59, v13
	v_fmac_f32_e32 v15, v45, v32
	v_fmac_f32_e32 v102, v60, v14
	ds_write_b32 v4, v33 offset:8448
	v_fmac_f32_e32 v102, v61, v15
	ds_write_b32 v118, v102 offset:9472
	s_waitcnt lgkmcnt(2)
	ds_read_b128 v[38:41], v0 offset:1280
	ds_read_b128 v[42:45], v0 offset:1296
	ds_read_b128 v[54:57], v0 offset:3328
	ds_read_b128 v[58:61], v0 offset:3344
	ds_read_b32 v32, v1 offset:4256
	v_fmac_f32_e32 v8, v22, v30
	v_fmac_f32_e32 v9, v23, v30
	v_mul_f32_e32 v36, v46, v8
	global_load_dwordx4 v[70:73], v5, s[94:95]
	global_load_dwordx4 v[74:77], v5, s[94:95] offset:512
	global_load_ushort v33, v6, s[94:95]
	v_add_u32_e32 v5, 0x6800, v5
	v_add_u32_e32 v6, 0x10000, v6
	v_fmac_f32_e32 v10, v24, v30
	v_fmac_f32_e32 v36, v47, v9
	v_fmac_f32_e32 v11, v25, v30
	ds_read_b128 v[124:127], v119 offset:10752
	v_fmac_f32_e32 v36, v48, v10
	v_fmac_f32_e32 v12, v26, v30
	v_fmac_f32_e32 v36, v49, v11
	ds_read_b128 v[128:131], v120 offset:10752
	v_fmac_f32_e32 v13, v27, v30
	v_fmac_f32_e32 v36, v50, v12
	v_fmac_f32_e32 v14, v28, v30
	v_fmac_f32_e32 v36, v51, v13
	v_fmac_f32_e32 v15, v29, v30
	v_fmac_f32_e32 v36, v52, v14
	v_fmac_f32_e32 v36, v53, v15
	ds_write_b32 v118, v36 offset:9728
	s_waitcnt lgkmcnt(3)
	ds_read_b128 v[22:25], v0 offset:1536
	ds_read_b128 v[26:29], v0 offset:1552
	ds_read_b128 v[46:49], v0 offset:3584
	ds_read_b128 v[50:53], v0 offset:3600
	ds_read_b32 v30, v1 offset:4288
	v_fmac_f32_e32 v8, v38, v32
	v_fmac_f32_e32 v9, v39, v32
	v_mul_f32_e32 v102, v54, v8
	v_fmac_f32_e32 v10, v40, v32
	v_fmac_f32_e32 v102, v55, v9
	v_fmac_f32_e32 v11, v41, v32
	v_fmac_f32_e32 v102, v56, v10
	v_fmac_f32_e32 v12, v42, v32
	v_fmac_f32_e32 v102, v57, v11
	v_fmac_f32_e32 v13, v43, v32
	v_fmac_f32_e32 v102, v58, v12
	v_fmac_f32_e32 v14, v44, v32
	v_fmac_f32_e32 v102, v59, v13
	v_fmac_f32_e32 v15, v45, v32
	v_fmac_f32_e32 v102, v60, v14
	v_fmac_f32_e32 v102, v61, v15
	ds_write_b32 v118, v102 offset:9984
	s_waitcnt lgkmcnt(1)
	ds_read_b128 v[38:41], v0 offset:1792
	ds_read_b128 v[42:45], v0 offset:1808
	ds_read_b128 v[54:57], v0 offset:3840
	ds_read_b128 v[58:61], v0 offset:3856
	ds_read_b32 v32, v1 offset:4320
	v_fmac_f32_e32 v8, v22, v30
	v_fmac_f32_e32 v9, v23, v30
	v_mul_f32_e32 v36, v46, v8
	s_waitcnt lgkmcnt(12)
	v_fmac_f32_e32 v10, v24, v30
	v_fmac_f32_e32 v36, v47, v9
	v_fmac_f32_e32 v11, v25, v30
	v_add_f32_e32 v124, v124, v128
	v_fmac_f32_e32 v36, v48, v10
	v_fmac_f32_e32 v12, v26, v30
	v_fmac_f32_e32 v36, v49, v11
	v_add_f32_e32 v125, v125, v129
	v_fmac_f32_e32 v13, v27, v30
	v_fmac_f32_e32 v36, v50, v12
	v_fmac_f32_e32 v14, v28, v30
	v_add_f32_e32 v126, v126, v130
	v_fmac_f32_e32 v36, v51, v13
	v_fmac_f32_e32 v15, v29, v30
	v_fmac_f32_e32 v36, v52, v14
	v_add_f32_e32 v127, v127, v131
	v_fmac_f32_e32 v36, v53, v15
	ds_write_b32 v118, v36 offset:10240
	v_add_f32_e32 v124, v124, v125
	v_add_f32_e32 v126, v126, v127
	v_add_f32_e32 v124, v124, v126
	v_mul_f32_e32 v124, v110, v124
	v_cvt_pk_bf16_f32 v21, v124, v124
	ds_write_b16 v112, v21 offset:13696
	v_add_u32_e32 v112, 0x200, v112
	s_and_b32 s24, s12, 15
	s_cmp_eq_u32 s24, 0
	s_cbranch_scc0 .Lls0_8_noflush
	s_cmp_eq_u32 s12, 64
	s_cbranch_scc1 .Lls0_8_noflush
	s_waitcnt lgkmcnt(0)
	ds_read_b128 v[114:117], v113 offset:13312
	s_waitcnt lgkmcnt(0)
	global_store_dwordx4 v7, v[114:117], s[94:95]
	v_add_u32_e32 v7, 0x20000, v7
	s_nop 0
	ds_read_b128 v[114:117], v113 offset:14336
	s_waitcnt lgkmcnt(0)
	global_store_dwordx4 v7, v[114:117], s[94:95]
	v_add_u32_e32 v7, 0x20000, v7
	s_nop 0
	ds_read_b128 v[114:117], v113 offset:15360
	s_waitcnt lgkmcnt(0)
	global_store_dwordx4 v7, v[114:117], s[94:95]
	v_add_u32_e32 v7, 0x20000, v7
	s_nop 0
	ds_read_b128 v[114:117], v113 offset:16384
	s_waitcnt lgkmcnt(0)
	global_store_dwordx4 v7, v[114:117], s[94:95]
	v_add_u32_e32 v7, 0x20000, v7
	s_nop 0
	ds_read_b128 v[114:117], v113 offset:17408
	s_waitcnt lgkmcnt(0)
	global_store_dwordx4 v7, v[114:117], s[94:95]
	v_add_u32_e32 v7, 0x20000, v7
	s_nop 0
	ds_read_b128 v[114:117], v113 offset:18432
	s_waitcnt lgkmcnt(0)
	global_store_dwordx4 v7, v[114:117], s[94:95]
	v_add_u32_e32 v7, 0x20000, v7
	s_nop 0
	ds_read_b128 v[114:117], v113 offset:19456
	s_waitcnt lgkmcnt(0)
	global_store_dwordx4 v7, v[114:117], s[94:95]
	v_add_u32_e32 v7, 0x20000, v7
	s_nop 0
	ds_read_b128 v[114:117], v113 offset:20480
	s_waitcnt lgkmcnt(0)
	global_store_dwordx4 v7, v[114:117], s[94:95]
	v_add_u32_e32 v7, 0x20000, v7
	s_nop 0
	v_subrev_u32_e32 v112, 0x2000, v112
.Lls0_8_noflush:
	s_waitcnt lgkmcnt(2)
	ds_read_b128 v[22:25], v0 offset:4352
	ds_read_b128 v[26:29], v0 offset:4368
	ds_read_b128 v[46:49], v0 offset:6400
	ds_read_b128 v[50:53], v0 offset:6416
	ds_read_b32 v30, v1 offset:8448
	v_fmac_f32_e32 v8, v38, v32
	v_fmac_f32_e32 v9, v39, v32
	v_mul_f32_e32 v102, v54, v8
	v_fmac_f32_e32 v10, v40, v32
	v_fmac_f32_e32 v102, v55, v9
	v_fmac_f32_e32 v11, v41, v32
	v_fmac_f32_e32 v102, v56, v10
	v_fmac_f32_e32 v12, v42, v32
	v_fmac_f32_e32 v102, v57, v11
	v_fmac_f32_e32 v13, v43, v32
	v_fmac_f32_e32 v102, v58, v12
	v_fmac_f32_e32 v14, v44, v32
	v_fmac_f32_e32 v102, v59, v13
	v_fmac_f32_e32 v15, v45, v32
	v_fmac_f32_e32 v102, v60, v14
	v_fmac_f32_e32 v102, v61, v15
	ds_write_b32 v118, v102 offset:10496
	s_waitcnt lgkmcnt(1)
	ds_read_b128 v[38:41], v0 offset:4608
	ds_read_b128 v[42:45], v0 offset:4624
	ds_read_b128 v[54:57], v0 offset:6656
	ds_read_b128 v[58:61], v0 offset:6672
	ds_read_b32 v32, v1 offset:8480
	v_fmac_f32_e32 v8, v22, v30
	v_fmac_f32_e32 v9, v23, v30
	v_mul_f32_e32 v36, v46, v8
	s_waitcnt vmcnt(10)
	v_fmac_f32_e32 v10, v24, v30
	v_fmac_f32_e32 v36, v47, v9
	v_fmac_f32_e32 v11, v25, v30
	v_lshlrev_b32_e32 v94, 16, v82
	v_fmac_f32_e32 v36, v48, v10
	v_fmac_f32_e32 v12, v26, v30
	v_fmac_f32_e32 v36, v49, v11
	v_and_b32_e32 v95, 0xffff0000, v82
	v_fmac_f32_e32 v13, v27, v30
	v_fmac_f32_e32 v36, v50, v12
	v_fmac_f32_e32 v14, v28, v30
	v_lshlrev_b32_e32 v96, 16, v83
	v_fmac_f32_e32 v36, v51, v13
	v_fmac_f32_e32 v15, v29, v30
	v_fmac_f32_e32 v36, v52, v14
	v_and_b32_e32 v97, 0xffff0000, v83
	v_fmac_f32_e32 v36, v53, v15
	ds_write_b32 v118, v36 offset:10752
	ds_write_b128 v2, v[94:97] offset:0
	v_lshlrev_b32_e32 v98, 16, v84
	s_waitcnt lgkmcnt(2)
	ds_read_b128 v[22:25], v0 offset:4864
	ds_read_b128 v[26:29], v0 offset:4880
	ds_read_b128 v[46:49], v0 offset:6912
	ds_read_b128 v[50:53], v0 offset:6928
	ds_read_b32 v30, v1 offset:8512
	v_fmac_f32_e32 v8, v38, v32
	v_fmac_f32_e32 v9, v39, v32
	v_mul_f32_e32 v102, v54, v8
	v_and_b32_e32 v99, 0xffff0000, v84
	v_fmac_f32_e32 v10, v40, v32
	v_fmac_f32_e32 v102, v55, v9
	v_fmac_f32_e32 v11, v41, v32
	v_lshlrev_b32_e32 v100, 16, v85
	v_fmac_f32_e32 v102, v56, v10
	v_fmac_f32_e32 v12, v42, v32
	v_fmac_f32_e32 v102, v57, v11
	v_and_b32_e32 v101, 0xffff0000, v85
	v_fmac_f32_e32 v13, v43, v32
	v_fmac_f32_e32 v102, v58, v12
	v_fmac_f32_e32 v14, v44, v32
	ds_write_b128 v2, v[98:101] offset:16
	v_fmac_f32_e32 v102, v59, v13
	v_fmac_f32_e32 v15, v45, v32
	v_fmac_f32_e32 v102, v60, v14
	v_lshlrev_b32_e32 v94, 16, v78
	v_fmac_f32_e32 v102, v61, v15
	ds_write_b32 v118, v102 offset:11008
	v_and_b32_e32 v95, 0xffff0000, v78
	v_lshlrev_b32_e32 v96, 16, v79
	s_waitcnt lgkmcnt(2)
	ds_read_b128 v[38:41], v0 offset:5120
	ds_read_b128 v[42:45], v0 offset:5136
	ds_read_b128 v[54:57], v0 offset:7168
	ds_read_b128 v[58:61], v0 offset:7184
	ds_read_b32 v32, v1 offset:8544
	v_fmac_f32_e32 v8, v22, v30
	v_fmac_f32_e32 v9, v23, v30
	v_mul_f32_e32 v36, v46, v8
	v_and_b32_e32 v97, 0xffff0000, v79
	v_fmac_f32_e32 v10, v24, v30
	v_fmac_f32_e32 v36, v47, v9
	v_fmac_f32_e32 v11, v25, v30
	ds_write_b128 v2, v[94:97] offset:2048
	v_fmac_f32_e32 v36, v48, v10
	v_fmac_f32_e32 v12, v26, v30
	v_fmac_f32_e32 v36, v49, v11
	v_lshlrev_b32_e32 v98, 16, v80
	v_fmac_f32_e32 v13, v27, v30
	v_fmac_f32_e32 v36, v50, v12
	v_fmac_f32_e32 v14, v28, v30
	v_and_b32_e32 v99, 0xffff0000, v80
	v_fmac_f32_e32 v36, v51, v13
	v_fmac_f32_e32 v15, v29, v30
	v_fmac_f32_e32 v36, v52, v14
	v_lshlrev_b32_e32 v100, 16, v81
	v_fmac_f32_e32 v36, v53, v15
	ds_write_b32 v118, v36 offset:11264
	v_and_b32_e32 v101, 0xffff0000, v81
	ds_write_b128 v2, v[98:101] offset:2064
	s_waitcnt lgkmcnt(3)
	ds_read_b128 v[22:25], v0 offset:5376
	ds_read_b128 v[26:29], v0 offset:5392
	ds_read_b128 v[46:49], v0 offset:7424
	ds_read_b128 v[50:53], v0 offset:7440
	ds_read_b32 v30, v1 offset:8576
	v_fmac_f32_e32 v8, v38, v32
	v_fmac_f32_e32 v9, v39, v32
	v_mul_f32_e32 v102, v54, v8
	s_waitcnt vmcnt(9)
	v_fmac_f32_e32 v10, v40, v32
	v_fmac_f32_e32 v102, v55, v9
	v_fmac_f32_e32 v11, v41, v32
	v_lshlrev_b32_e32 v34, 16, v34
	v_fmac_f32_e32 v102, v56, v10
	v_fmac_f32_e32 v12, v42, v32
	v_fmac_f32_e32 v102, v57, v11
	v_mul_f32_e32 v34, v105, v34
	v_fmac_f32_e32 v13, v43, v32
	v_fmac_f32_e32 v102, v58, v12
	v_fmac_f32_e32 v14, v44, v32
	s_nop 0
	v_fmac_f32_e32 v102, v59, v13
	v_fmac_f32_e32 v15, v45, v32
	v_fmac_f32_e32 v102, v60, v14
	ds_write_b32 v4, v34 offset:4096
	v_fmac_f32_e32 v102, v61, v15
	ds_write_b32 v118, v102 offset:11520
	s_waitcnt lgkmcnt(2)
	ds_read_b128 v[38:41], v0 offset:5632
	ds_read_b128 v[42:45], v0 offset:5648
	ds_read_b128 v[54:57], v0 offset:7680
	ds_read_b128 v[58:61], v0 offset:7696
	ds_read_b32 v32, v1 offset:8608
	v_fmac_f32_e32 v8, v22, v30
	v_fmac_f32_e32 v9, v23, v30
	v_mul_f32_e32 v36, v46, v8
	global_load_dwordx4 v[78:81], v5, s[94:95]
	global_load_dwordx4 v[82:85], v5, s[94:95] offset:512
	global_load_ushort v34, v6, s[94:95]
	v_add_u32_e32 v5, 0x6800, v5
	v_add_u32_e32 v6, 0x10000, v6
	v_fmac_f32_e32 v10, v24, v30
	v_fmac_f32_e32 v36, v47, v9
	v_fmac_f32_e32 v11, v25, v30
	ds_read_b128 v[124:127], v119 offset:8704
	v_fmac_f32_e32 v36, v48, v10
	v_fmac_f32_e32 v12, v26, v30
	v_fmac_f32_e32 v36, v49, v11
	ds_read_b128 v[128:131], v120 offset:8704
	v_fmac_f32_e32 v13, v27, v30
	v_fmac_f32_e32 v36, v50, v12
	v_fmac_f32_e32 v14, v28, v30
	v_fmac_f32_e32 v36, v51, v13
	v_fmac_f32_e32 v15, v29, v30
	v_fmac_f32_e32 v36, v52, v14
	v_fmac_f32_e32 v36, v53, v15
	ds_write_b32 v118, v36 offset:11776
	s_waitcnt lgkmcnt(3)
	ds_read_b128 v[22:25], v0 offset:5888
	ds_read_b128 v[26:29], v0 offset:5904
	ds_read_b128 v[46:49], v0 offset:7936
	ds_read_b128 v[50:53], v0 offset:7952
	ds_read_b32 v30, v1 offset:8640
	v_fmac_f32_e32 v8, v38, v32
	v_fmac_f32_e32 v9, v39, v32
	v_mul_f32_e32 v102, v54, v8
	v_fmac_f32_e32 v10, v40, v32
	v_fmac_f32_e32 v102, v55, v9
	v_fmac_f32_e32 v11, v41, v32
	v_fmac_f32_e32 v102, v56, v10
	v_fmac_f32_e32 v12, v42, v32
	v_fmac_f32_e32 v102, v57, v11
	v_fmac_f32_e32 v13, v43, v32
	v_fmac_f32_e32 v102, v58, v12
	v_fmac_f32_e32 v14, v44, v32
	v_fmac_f32_e32 v102, v59, v13
	v_fmac_f32_e32 v15, v45, v32
	v_fmac_f32_e32 v102, v60, v14
	v_fmac_f32_e32 v102, v61, v15
	ds_write_b32 v118, v102 offset:12032
	s_waitcnt lgkmcnt(1)
	ds_read_b128 v[38:41], v0 offset:6144
	ds_read_b128 v[42:45], v0 offset:6160
	ds_read_b128 v[54:57], v0 offset:8192
	ds_read_b128 v[58:61], v0 offset:8208
	ds_read_b32 v32, v1 offset:8672
	v_fmac_f32_e32 v8, v22, v30
	v_fmac_f32_e32 v9, v23, v30
	v_mul_f32_e32 v36, v46, v8
	s_waitcnt lgkmcnt(12)
	v_fmac_f32_e32 v10, v24, v30
	v_fmac_f32_e32 v36, v47, v9
	v_fmac_f32_e32 v11, v25, v30
	v_add_f32_e32 v124, v124, v128
	v_fmac_f32_e32 v36, v48, v10
	v_fmac_f32_e32 v12, v26, v30
	v_fmac_f32_e32 v36, v49, v11
	v_add_f32_e32 v125, v125, v129
	v_fmac_f32_e32 v13, v27, v30
	v_fmac_f32_e32 v36, v50, v12
	v_fmac_f32_e32 v14, v28, v30
	v_add_f32_e32 v126, v126, v130
	v_fmac_f32_e32 v36, v51, v13
	v_fmac_f32_e32 v15, v29, v30
	v_fmac_f32_e32 v36, v52, v14
	v_add_f32_e32 v127, v127, v131
	v_fmac_f32_e32 v36, v53, v15
	ds_write_b32 v118, v36 offset:12288
	v_add_f32_e32 v124, v124, v125
	v_add_f32_e32 v126, v126, v127
	v_add_f32_e32 v124, v124, v126
	v_mul_f32_e32 v124, v107, v124
	v_cvt_pk_bf16_f32 v21, v124, v124
	ds_write_b16 v112, v21 offset:13312
	s_waitcnt lgkmcnt(2)
	ds_read_b128 v[22:25], v0 offset:0
	ds_read_b128 v[26:29], v0 offset:16
	ds_read_b128 v[46:49], v0 offset:2048
	ds_read_b128 v[50:53], v0 offset:2064
	ds_read_b32 v30, v1 offset:4096
	v_fmac_f32_e32 v8, v38, v32
	v_fmac_f32_e32 v9, v39, v32
	v_mul_f32_e32 v102, v54, v8
	v_fmac_f32_e32 v10, v40, v32
	v_fmac_f32_e32 v102, v55, v9
	v_fmac_f32_e32 v11, v41, v32
	v_fmac_f32_e32 v102, v56, v10
	v_fmac_f32_e32 v12, v42, v32
	v_fmac_f32_e32 v102, v57, v11
	v_fmac_f32_e32 v13, v43, v32
	v_fmac_f32_e32 v102, v58, v12
	v_fmac_f32_e32 v14, v44, v32
	v_fmac_f32_e32 v102, v59, v13
	v_fmac_f32_e32 v15, v45, v32
	v_fmac_f32_e32 v102, v60, v14
	v_fmac_f32_e32 v102, v61, v15
	ds_write_b32 v118, v102 offset:12544
	s_waitcnt lgkmcnt(1)
	ds_read_b128 v[38:41], v0 offset:256
	ds_read_b128 v[42:45], v0 offset:272
	ds_read_b128 v[54:57], v0 offset:2304
	ds_read_b128 v[58:61], v0 offset:2320
	ds_read_b32 v32, v1 offset:4128
	v_fmac_f32_e32 v8, v22, v30
	v_fmac_f32_e32 v9, v23, v30
	v_mul_f32_e32 v36, v46, v8
	s_waitcnt vmcnt(10)
	v_fmac_f32_e32 v10, v24, v30
	v_fmac_f32_e32 v36, v47, v9
	v_fmac_f32_e32 v11, v25, v30
	v_lshlrev_b32_e32 v94, 16, v90
	v_fmac_f32_e32 v36, v48, v10
	v_fmac_f32_e32 v12, v26, v30
	v_fmac_f32_e32 v36, v49, v11
	v_and_b32_e32 v95, 0xffff0000, v90
	v_fmac_f32_e32 v13, v27, v30
	v_fmac_f32_e32 v36, v50, v12
	v_fmac_f32_e32 v14, v28, v30
	v_lshlrev_b32_e32 v96, 16, v91
	v_fmac_f32_e32 v36, v51, v13
	v_fmac_f32_e32 v15, v29, v30
	v_fmac_f32_e32 v36, v52, v14
	v_and_b32_e32 v97, 0xffff0000, v91
	v_fmac_f32_e32 v36, v53, v15
	ds_write_b32 v118, v36 offset:8704
	ds_write_b128 v2, v[94:97] offset:4352
	v_lshlrev_b32_e32 v98, 16, v92
	s_waitcnt lgkmcnt(2)
	ds_read_b128 v[22:25], v0 offset:512
	ds_read_b128 v[26:29], v0 offset:528
	ds_read_b128 v[46:49], v0 offset:2560
	ds_read_b128 v[50:53], v0 offset:2576
	ds_read_b32 v30, v1 offset:4160
	v_fmac_f32_e32 v8, v38, v32
	v_fmac_f32_e32 v9, v39, v32
	v_mul_f32_e32 v102, v54, v8
	v_and_b32_e32 v99, 0xffff0000, v92
	v_fmac_f32_e32 v10, v40, v32
	v_fmac_f32_e32 v102, v55, v9
	v_fmac_f32_e32 v11, v41, v32
	v_lshlrev_b32_e32 v100, 16, v93
	v_fmac_f32_e32 v102, v56, v10
	v_fmac_f32_e32 v12, v42, v32
	v_fmac_f32_e32 v102, v57, v11
	v_and_b32_e32 v101, 0xffff0000, v93
	v_fmac_f32_e32 v13, v43, v32
	v_fmac_f32_e32 v102, v58, v12
	v_fmac_f32_e32 v14, v44, v32
	ds_write_b128 v2, v[98:101] offset:4368
	v_fmac_f32_e32 v102, v59, v13
	v_fmac_f32_e32 v15, v45, v32
	v_fmac_f32_e32 v102, v60, v14
	v_lshlrev_b32_e32 v94, 16, v86
	v_fmac_f32_e32 v102, v61, v15
	ds_write_b32 v118, v102 offset:8960
	v_and_b32_e32 v95, 0xffff0000, v86
	v_lshlrev_b32_e32 v96, 16, v87
	s_waitcnt lgkmcnt(2)
	ds_read_b128 v[38:41], v0 offset:768
	ds_read_b128 v[42:45], v0 offset:784
	ds_read_b128 v[54:57], v0 offset:2816
	ds_read_b128 v[58:61], v0 offset:2832
	ds_read_b32 v32, v1 offset:4192
	v_fmac_f32_e32 v8, v22, v30
	v_fmac_f32_e32 v9, v23, v30
	v_mul_f32_e32 v36, v46, v8
	v_and_b32_e32 v97, 0xffff0000, v87
	v_fmac_f32_e32 v10, v24, v30
	v_fmac_f32_e32 v36, v47, v9
	v_fmac_f32_e32 v11, v25, v30
	ds_write_b128 v2, v[94:97] offset:6400
	v_fmac_f32_e32 v36, v48, v10
	v_fmac_f32_e32 v12, v26, v30
	v_fmac_f32_e32 v36, v49, v11
	v_lshlrev_b32_e32 v98, 16, v88
	v_fmac_f32_e32 v13, v27, v30
	v_fmac_f32_e32 v36, v50, v12
	v_fmac_f32_e32 v14, v28, v30
	v_and_b32_e32 v99, 0xffff0000, v88
	v_fmac_f32_e32 v36, v51, v13
	v_fmac_f32_e32 v15, v29, v30
	v_fmac_f32_e32 v36, v52, v14
	v_lshlrev_b32_e32 v100, 16, v89
	v_fmac_f32_e32 v36, v53, v15
	ds_write_b32 v118, v36 offset:9216
	v_and_b32_e32 v101, 0xffff0000, v89
	ds_write_b128 v2, v[98:101] offset:6416
	s_waitcnt lgkmcnt(3)
	ds_read_b128 v[22:25], v0 offset:1024
	ds_read_b128 v[26:29], v0 offset:1040
	ds_read_b128 v[46:49], v0 offset:3072
	ds_read_b128 v[50:53], v0 offset:3088
	ds_read_b32 v30, v1 offset:4224
	v_fmac_f32_e32 v8, v38, v32
	v_fmac_f32_e32 v9, v39, v32
	v_mul_f32_e32 v102, v54, v8
	s_waitcnt vmcnt(9)
	v_fmac_f32_e32 v10, v40, v32
	v_fmac_f32_e32 v102, v55, v9
	v_fmac_f32_e32 v11, v41, v32
	v_lshlrev_b32_e32 v35, 16, v35
	v_fmac_f32_e32 v102, v56, v10
	v_fmac_f32_e32 v12, v42, v32
	v_fmac_f32_e32 v102, v57, v11
	v_mul_f32_e32 v35, v106, v35
	v_fmac_f32_e32 v13, v43, v32
	v_fmac_f32_e32 v102, v58, v12
	v_fmac_f32_e32 v14, v44, v32
	s_nop 0
	v_fmac_f32_e32 v102, v59, v13
	v_fmac_f32_e32 v15, v45, v32
	v_fmac_f32_e32 v102, v60, v14
	ds_write_b32 v4, v35 offset:8448
	v_fmac_f32_e32 v102, v61, v15
	ds_write_b32 v118, v102 offset:9472
	s_waitcnt lgkmcnt(2)
	ds_read_b128 v[38:41], v0 offset:1280
	ds_read_b128 v[42:45], v0 offset:1296
	ds_read_b128 v[54:57], v0 offset:3328
	ds_read_b128 v[58:61], v0 offset:3344
	ds_read_b32 v32, v1 offset:4256
	v_fmac_f32_e32 v8, v22, v30
	v_fmac_f32_e32 v9, v23, v30
	v_mul_f32_e32 v36, v46, v8
	global_load_dwordx4 v[86:89], v5, s[94:95]
	global_load_dwordx4 v[90:93], v5, s[94:95] offset:512
	global_load_ushort v35, v6, s[94:95]
	v_add_u32_e32 v5, 0x6800, v5
	v_add_u32_e32 v6, 0x10000, v6
	v_fmac_f32_e32 v10, v24, v30
	v_fmac_f32_e32 v36, v47, v9
	v_fmac_f32_e32 v11, v25, v30
	ds_read_b128 v[124:127], v119 offset:10752
	v_fmac_f32_e32 v36, v48, v10
	v_fmac_f32_e32 v12, v26, v30
	v_fmac_f32_e32 v36, v49, v11
	ds_read_b128 v[128:131], v120 offset:10752
	v_fmac_f32_e32 v13, v27, v30
	v_fmac_f32_e32 v36, v50, v12
	v_fmac_f32_e32 v14, v28, v30
	v_fmac_f32_e32 v36, v51, v13
	v_fmac_f32_e32 v15, v29, v30
	v_fmac_f32_e32 v36, v52, v14
	v_fmac_f32_e32 v36, v53, v15
	ds_write_b32 v118, v36 offset:9728
	s_waitcnt lgkmcnt(3)
	ds_read_b128 v[22:25], v0 offset:1536
	ds_read_b128 v[26:29], v0 offset:1552
	ds_read_b128 v[46:49], v0 offset:3584
	ds_read_b128 v[50:53], v0 offset:3600
	ds_read_b32 v30, v1 offset:4288
	v_fmac_f32_e32 v8, v38, v32
	v_fmac_f32_e32 v9, v39, v32
	v_mul_f32_e32 v102, v54, v8
	v_fmac_f32_e32 v10, v40, v32
	v_fmac_f32_e32 v102, v55, v9
	v_fmac_f32_e32 v11, v41, v32
	v_fmac_f32_e32 v102, v56, v10
	v_fmac_f32_e32 v12, v42, v32
	v_fmac_f32_e32 v102, v57, v11
	v_fmac_f32_e32 v13, v43, v32
	v_fmac_f32_e32 v102, v58, v12
	v_fmac_f32_e32 v14, v44, v32
	v_fmac_f32_e32 v102, v59, v13
	v_fmac_f32_e32 v15, v45, v32
	v_fmac_f32_e32 v102, v60, v14
	v_fmac_f32_e32 v102, v61, v15
	ds_write_b32 v118, v102 offset:9984
	s_waitcnt lgkmcnt(1)
	ds_read_b128 v[38:41], v0 offset:1792
	ds_read_b128 v[42:45], v0 offset:1808
	ds_read_b128 v[54:57], v0 offset:3840
	ds_read_b128 v[58:61], v0 offset:3856
	ds_read_b32 v32, v1 offset:4320
	v_fmac_f32_e32 v8, v22, v30
	v_fmac_f32_e32 v9, v23, v30
	v_mul_f32_e32 v36, v46, v8
	s_waitcnt lgkmcnt(12)
	v_fmac_f32_e32 v10, v24, v30
	v_fmac_f32_e32 v36, v47, v9
	v_fmac_f32_e32 v11, v25, v30
	v_add_f32_e32 v124, v124, v128
	v_fmac_f32_e32 v36, v48, v10
	v_fmac_f32_e32 v12, v26, v30
	v_fmac_f32_e32 v36, v49, v11
	v_add_f32_e32 v125, v125, v129
	v_fmac_f32_e32 v13, v27, v30
	v_fmac_f32_e32 v36, v50, v12
	v_fmac_f32_e32 v14, v28, v30
	v_add_f32_e32 v126, v126, v130
	v_fmac_f32_e32 v36, v51, v13
	v_fmac_f32_e32 v15, v29, v30
	v_fmac_f32_e32 v36, v52, v14
	v_add_f32_e32 v127, v127, v131
	v_fmac_f32_e32 v36, v53, v15
	ds_write_b32 v118, v36 offset:10240
	v_add_f32_e32 v124, v124, v125
	v_add_f32_e32 v126, v126, v127
	v_add_f32_e32 v124, v124, v126
	v_mul_f32_e32 v124, v108, v124
	v_cvt_pk_bf16_f32 v21, v124, v124
	ds_write_b16 v112, v21 offset:13440
	s_waitcnt lgkmcnt(2)
	ds_read_b128 v[22:25], v0 offset:4352
	ds_read_b128 v[26:29], v0 offset:4368
	ds_read_b128 v[46:49], v0 offset:6400
	ds_read_b128 v[50:53], v0 offset:6416
	ds_read_b32 v30, v1 offset:8448
	v_fmac_f32_e32 v8, v38, v32
	v_fmac_f32_e32 v9, v39, v32
	v_mul_f32_e32 v102, v54, v8
	v_fmac_f32_e32 v10, v40, v32
	v_fmac_f32_e32 v102, v55, v9
	v_fmac_f32_e32 v11, v41, v32
	v_fmac_f32_e32 v102, v56, v10
	v_fmac_f32_e32 v12, v42, v32
	v_fmac_f32_e32 v102, v57, v11
	v_fmac_f32_e32 v13, v43, v32
	v_fmac_f32_e32 v102, v58, v12
	v_fmac_f32_e32 v14, v44, v32
	v_fmac_f32_e32 v102, v59, v13
	v_fmac_f32_e32 v15, v45, v32
	v_fmac_f32_e32 v102, v60, v14
	v_fmac_f32_e32 v102, v61, v15
	ds_write_b32 v118, v102 offset:10496
	s_waitcnt lgkmcnt(1)
	ds_read_b128 v[38:41], v0 offset:4608
	ds_read_b128 v[42:45], v0 offset:4624
	ds_read_b128 v[54:57], v0 offset:6656
	ds_read_b128 v[58:61], v0 offset:6672
	ds_read_b32 v32, v1 offset:8480
	v_fmac_f32_e32 v8, v22, v30
	v_fmac_f32_e32 v9, v23, v30
	v_mul_f32_e32 v36, v46, v8
	s_waitcnt vmcnt(10)
	v_fmac_f32_e32 v10, v24, v30
	v_fmac_f32_e32 v36, v47, v9
	v_fmac_f32_e32 v11, v25, v30
	v_lshlrev_b32_e32 v94, 16, v66
	v_fmac_f32_e32 v36, v48, v10
	v_fmac_f32_e32 v12, v26, v30
	v_fmac_f32_e32 v36, v49, v11
	v_and_b32_e32 v95, 0xffff0000, v66
	v_fmac_f32_e32 v13, v27, v30
	v_fmac_f32_e32 v36, v50, v12
	v_fmac_f32_e32 v14, v28, v30
	v_lshlrev_b32_e32 v96, 16, v67
	v_fmac_f32_e32 v36, v51, v13
	v_fmac_f32_e32 v15, v29, v30
	v_fmac_f32_e32 v36, v52, v14
	v_and_b32_e32 v97, 0xffff0000, v67
	v_fmac_f32_e32 v36, v53, v15
	ds_write_b32 v118, v36 offset:10752
	ds_write_b128 v2, v[94:97] offset:0
	v_lshlrev_b32_e32 v98, 16, v68
	s_waitcnt lgkmcnt(2)
	ds_read_b128 v[22:25], v0 offset:4864
	ds_read_b128 v[26:29], v0 offset:4880
	ds_read_b128 v[46:49], v0 offset:6912
	ds_read_b128 v[50:53], v0 offset:6928
	ds_read_b32 v30, v1 offset:8512
	v_fmac_f32_e32 v8, v38, v32
	v_fmac_f32_e32 v9, v39, v32
	v_mul_f32_e32 v102, v54, v8
	v_and_b32_e32 v99, 0xffff0000, v68
	v_fmac_f32_e32 v10, v40, v32
	v_fmac_f32_e32 v102, v55, v9
	v_fmac_f32_e32 v11, v41, v32
	v_lshlrev_b32_e32 v100, 16, v69
	v_fmac_f32_e32 v102, v56, v10
	v_fmac_f32_e32 v12, v42, v32
	v_fmac_f32_e32 v102, v57, v11
	v_and_b32_e32 v101, 0xffff0000, v69
	v_fmac_f32_e32 v13, v43, v32
	v_fmac_f32_e32 v102, v58, v12
	v_fmac_f32_e32 v14, v44, v32
	ds_write_b128 v2, v[98:101] offset:16
	v_fmac_f32_e32 v102, v59, v13
	v_fmac_f32_e32 v15, v45, v32
	v_fmac_f32_e32 v102, v60, v14
	v_lshlrev_b32_e32 v94, 16, v62
	v_fmac_f32_e32 v102, v61, v15
	ds_write_b32 v118, v102 offset:11008
	v_and_b32_e32 v95, 0xffff0000, v62
	v_lshlrev_b32_e32 v96, 16, v63
	s_waitcnt lgkmcnt(2)
	ds_read_b128 v[38:41], v0 offset:5120
	ds_read_b128 v[42:45], v0 offset:5136
	ds_read_b128 v[54:57], v0 offset:7168
	ds_read_b128 v[58:61], v0 offset:7184
	ds_read_b32 v32, v1 offset:8544
	v_fmac_f32_e32 v8, v22, v30
	v_fmac_f32_e32 v9, v23, v30
	v_mul_f32_e32 v36, v46, v8
	v_and_b32_e32 v97, 0xffff0000, v63
	v_fmac_f32_e32 v10, v24, v30
	v_fmac_f32_e32 v36, v47, v9
	v_fmac_f32_e32 v11, v25, v30
	ds_write_b128 v2, v[94:97] offset:2048
	v_fmac_f32_e32 v36, v48, v10
	v_fmac_f32_e32 v12, v26, v30
	v_fmac_f32_e32 v36, v49, v11
	v_lshlrev_b32_e32 v98, 16, v64
	v_fmac_f32_e32 v13, v27, v30
	v_fmac_f32_e32 v36, v50, v12
	v_fmac_f32_e32 v14, v28, v30
	v_and_b32_e32 v99, 0xffff0000, v64
	v_fmac_f32_e32 v36, v51, v13
	v_fmac_f32_e32 v15, v29, v30
	v_fmac_f32_e32 v36, v52, v14
	v_lshlrev_b32_e32 v100, 16, v65
	v_fmac_f32_e32 v36, v53, v15
	ds_write_b32 v118, v36 offset:11264
	v_and_b32_e32 v101, 0xffff0000, v65
	ds_write_b128 v2, v[98:101] offset:2064
	s_waitcnt lgkmcnt(3)
	ds_read_b128 v[22:25], v0 offset:5376
	ds_read_b128 v[26:29], v0 offset:5392
	ds_read_b128 v[46:49], v0 offset:7424
	ds_read_b128 v[50:53], v0 offset:7440
	ds_read_b32 v30, v1 offset:8576
	v_fmac_f32_e32 v8, v38, v32
	v_fmac_f32_e32 v9, v39, v32
	v_mul_f32_e32 v102, v54, v8
	s_waitcnt vmcnt(9)
	v_fmac_f32_e32 v10, v40, v32
	v_fmac_f32_e32 v102, v55, v9
	v_fmac_f32_e32 v11, v41, v32
	v_lshlrev_b32_e32 v31, 16, v31
	v_fmac_f32_e32 v102, v56, v10
	v_fmac_f32_e32 v12, v42, v32
	v_fmac_f32_e32 v102, v57, v11
	v_mul_f32_e32 v31, v103, v31
	v_fmac_f32_e32 v13, v43, v32
	v_fmac_f32_e32 v102, v58, v12
	v_fmac_f32_e32 v14, v44, v32
	s_nop 0
	v_fmac_f32_e32 v102, v59, v13
	v_fmac_f32_e32 v15, v45, v32
	v_fmac_f32_e32 v102, v60, v14
	ds_write_b32 v4, v31 offset:4096
	v_fmac_f32_e32 v102, v61, v15
	ds_write_b32 v118, v102 offset:11520
	s_waitcnt lgkmcnt(2)
	ds_read_b128 v[38:41], v0 offset:5632
	ds_read_b128 v[42:45], v0 offset:5648
	ds_read_b128 v[54:57], v0 offset:7680
	ds_read_b128 v[58:61], v0 offset:7696
	ds_read_b32 v32, v1 offset:8608
	v_fmac_f32_e32 v8, v22, v30
	v_fmac_f32_e32 v9, v23, v30
	v_mul_f32_e32 v36, v46, v8
	global_load_dwordx4 v[62:65], v5, s[94:95]
	global_load_dwordx4 v[66:69], v5, s[94:95] offset:512
	global_load_ushort v31, v6, s[94:95]
	v_add_u32_e32 v5, 0x6800, v5
	v_add_u32_e32 v6, 0x10000, v6
	v_fmac_f32_e32 v10, v24, v30
	v_fmac_f32_e32 v36, v47, v9
	v_fmac_f32_e32 v11, v25, v30
	ds_read_b128 v[124:127], v119 offset:8704
	v_fmac_f32_e32 v36, v48, v10
	v_fmac_f32_e32 v12, v26, v30
	v_fmac_f32_e32 v36, v49, v11
	ds_read_b128 v[128:131], v120 offset:8704
	v_fmac_f32_e32 v13, v27, v30
	v_fmac_f32_e32 v36, v50, v12
	v_fmac_f32_e32 v14, v28, v30
	v_fmac_f32_e32 v36, v51, v13
	v_fmac_f32_e32 v15, v29, v30
	v_fmac_f32_e32 v36, v52, v14
	v_fmac_f32_e32 v36, v53, v15
	ds_write_b32 v118, v36 offset:11776
	s_waitcnt lgkmcnt(3)
	ds_read_b128 v[22:25], v0 offset:5888
	ds_read_b128 v[26:29], v0 offset:5904
	ds_read_b128 v[46:49], v0 offset:7936
	ds_read_b128 v[50:53], v0 offset:7952
	ds_read_b32 v30, v1 offset:8640
	v_fmac_f32_e32 v8, v38, v32
	v_fmac_f32_e32 v9, v39, v32
	v_mul_f32_e32 v102, v54, v8
	v_fmac_f32_e32 v10, v40, v32
	v_fmac_f32_e32 v102, v55, v9
	v_fmac_f32_e32 v11, v41, v32
	v_fmac_f32_e32 v102, v56, v10
	v_fmac_f32_e32 v12, v42, v32
	v_fmac_f32_e32 v102, v57, v11
	v_fmac_f32_e32 v13, v43, v32
	v_fmac_f32_e32 v102, v58, v12
	v_fmac_f32_e32 v14, v44, v32
	v_fmac_f32_e32 v102, v59, v13
	v_fmac_f32_e32 v15, v45, v32
	v_fmac_f32_e32 v102, v60, v14
	v_fmac_f32_e32 v102, v61, v15
	ds_write_b32 v118, v102 offset:12032
	s_waitcnt lgkmcnt(1)
	ds_read_b128 v[38:41], v0 offset:6144
	ds_read_b128 v[42:45], v0 offset:6160
	ds_read_b128 v[54:57], v0 offset:8192
	ds_read_b128 v[58:61], v0 offset:8208
	ds_read_b32 v32, v1 offset:8672
	v_fmac_f32_e32 v8, v22, v30
	v_fmac_f32_e32 v9, v23, v30
	v_mul_f32_e32 v36, v46, v8
	s_waitcnt lgkmcnt(12)
	v_fmac_f32_e32 v10, v24, v30
	v_fmac_f32_e32 v36, v47, v9
	v_fmac_f32_e32 v11, v25, v30
	v_add_f32_e32 v124, v124, v128
	v_fmac_f32_e32 v36, v48, v10
	v_fmac_f32_e32 v12, v26, v30
	v_fmac_f32_e32 v36, v49, v11
	v_add_f32_e32 v125, v125, v129
	v_fmac_f32_e32 v13, v27, v30
	v_fmac_f32_e32 v36, v50, v12
	v_fmac_f32_e32 v14, v28, v30
	v_add_f32_e32 v126, v126, v130
	v_fmac_f32_e32 v36, v51, v13
	v_fmac_f32_e32 v15, v29, v30
	v_fmac_f32_e32 v36, v52, v14
	v_add_f32_e32 v127, v127, v131
	v_fmac_f32_e32 v36, v53, v15
	ds_write_b32 v118, v36 offset:12288
	v_add_f32_e32 v124, v124, v125
	v_add_f32_e32 v126, v126, v127
	v_add_f32_e32 v124, v124, v126
	v_mul_f32_e32 v124, v109, v124
	v_cvt_pk_bf16_f32 v21, v124, v124
	ds_write_b16 v112, v21 offset:13568
	s_waitcnt lgkmcnt(2)
	ds_read_b128 v[22:25], v0 offset:0
	ds_read_b128 v[26:29], v0 offset:16
	ds_read_b128 v[46:49], v0 offset:2048
	ds_read_b128 v[50:53], v0 offset:2064
	ds_read_b32 v30, v1 offset:4096
	v_fmac_f32_e32 v8, v38, v32
	v_fmac_f32_e32 v9, v39, v32
	v_mul_f32_e32 v102, v54, v8
	v_fmac_f32_e32 v10, v40, v32
	v_fmac_f32_e32 v102, v55, v9
	v_fmac_f32_e32 v11, v41, v32
	v_fmac_f32_e32 v102, v56, v10
	v_fmac_f32_e32 v12, v42, v32
	v_fmac_f32_e32 v102, v57, v11
	v_fmac_f32_e32 v13, v43, v32
	v_fmac_f32_e32 v102, v58, v12
	v_fmac_f32_e32 v14, v44, v32
	v_fmac_f32_e32 v102, v59, v13
	v_fmac_f32_e32 v15, v45, v32
	v_fmac_f32_e32 v102, v60, v14
	v_fmac_f32_e32 v102, v61, v15
	ds_write_b32 v118, v102 offset:12544
	v_mul_f32_e32 v8, s44, v8
	v_mul_f32_e32 v9, s44, v9
	v_mul_f32_e32 v10, s44, v10
	v_mul_f32_e32 v11, s44, v11
	v_mul_f32_e32 v12, s44, v12
	v_mul_f32_e32 v13, s44, v13
	v_mul_f32_e32 v14, s44, v14
	v_mul_f32_e32 v15, s44, v15
	s_sub_u32 s12, s12, 1
	s_cmp_lg_u32 s12, 0
	s_cbranch_scc1 .Lls0_8_loop
	ds_read_b128 v[124:127], v119 offset:10752
	ds_read_b128 v[128:131], v120 offset:10752
	s_waitcnt lgkmcnt(0)
	v_add_f32_e32 v124, v124, v128
	v_add_f32_e32 v125, v125, v129
	v_add_f32_e32 v126, v126, v130
	v_add_f32_e32 v127, v127, v131
	v_add_f32_e32 v124, v124, v125
	v_add_f32_e32 v126, v126, v127
	v_add_f32_e32 v124, v124, v126
	v_mul_f32_e32 v124, v110, v124
	v_cvt_pk_bf16_f32 v21, v124, v124
	ds_write_b16 v112, v21 offset:13696
	s_waitcnt lgkmcnt(0)
	ds_read_b128 v[114:117], v113 offset:13312
	s_waitcnt lgkmcnt(0)
	global_store_dwordx4 v7, v[114:117], s[94:95]
	v_add_u32_e32 v7, 0x20000, v7
	s_nop 0
	ds_read_b128 v[114:117], v113 offset:14336
	s_waitcnt lgkmcnt(0)
	global_store_dwordx4 v7, v[114:117], s[94:95]
	v_add_u32_e32 v7, 0x20000, v7
	s_nop 0
	ds_read_b128 v[114:117], v113 offset:15360
	s_waitcnt lgkmcnt(0)
	global_store_dwordx4 v7, v[114:117], s[94:95]
	v_add_u32_e32 v7, 0x20000, v7
	s_nop 0
	ds_read_b128 v[114:117], v113 offset:16384
	s_waitcnt lgkmcnt(0)
	global_store_dwordx4 v7, v[114:117], s[94:95]
	v_add_u32_e32 v7, 0x20000, v7
	s_nop 0
	ds_read_b128 v[114:117], v113 offset:17408
	s_waitcnt lgkmcnt(0)
	global_store_dwordx4 v7, v[114:117], s[94:95]
	v_add_u32_e32 v7, 0x20000, v7
	s_nop 0
	ds_read_b128 v[114:117], v113 offset:18432
	s_waitcnt lgkmcnt(0)
	global_store_dwordx4 v7, v[114:117], s[94:95]
	v_add_u32_e32 v7, 0x20000, v7
	s_nop 0
	ds_read_b128 v[114:117], v113 offset:19456
	s_waitcnt lgkmcnt(0)
	global_store_dwordx4 v7, v[114:117], s[94:95]
	v_add_u32_e32 v7, 0x20000, v7
	s_nop 0
	ds_read_b128 v[114:117], v113 offset:20480
	s_waitcnt lgkmcnt(0)
	global_store_dwordx4 v7, v[114:117], s[94:95]
	v_add_u32_e32 v7, 0x20000, v7
	s_nop 0
	global_store_dword v111, v8, s[26:27] offset:0
	global_store_dword v111, v9, s[26:27] offset:256
	global_store_dword v111, v10, s[26:27] offset:512
	global_store_dword v111, v11, s[26:27] offset:768
	global_store_dword v111, v12, s[26:27] offset:1024
	global_store_dword v111, v13, s[26:27] offset:1280
	global_store_dword v111, v14, s[26:27] offset:1536
	global_store_dword v111, v15, s[26:27] offset:1792
	s_waitcnt vmcnt(0) lgkmcnt(0)
	s_setprio 0
	s_branch .Lls_done
